# sample item: V rows of each selected/window batch requested together with the K rows (fresh registers v150-181), copied into place at the original waits
# speedup vs baseline: 1.0030x; 1.0016x over previous
; __device__ __forceinline__ float dot4(f32x4 a, f32x4 b) { return (a[0] * b[0] + a[1] * b[1]) + (a[2] * b[2] + a[3] * b[3]); }
; __device__ __forceinline__ float grp16_sum(float v) { return sum16(v); }
; __device__ __forceinline__ void smp_batch(const f32x4 (&kx)[8], const f32x4 (&vx)[8], const f32x4 (&qv)[4], float (&m)[4], float (&l)[4], f32x4 (&o)[4]) {
; #pragma unroll
;     for (int h = 0; h < 4; ++h) { float s[8];
; #pragma unroll
;         for (int u = 0; u < 8; ++u) s[u] = grp16_sum(dot4(kx[u], qv[h]));
; __device__ __forceinline__ void attn_sample_item(const SmpArgs& a, int b, int g, LAS unsigned char* lds, int tid) {
;     ...
;               for (int it8 = 0; it8 < 2; ++it8) { const float* p0 = base + (size_t)it8 * 32 * 1024; f32x4 kx[8], vx[8];
; #pragma unroll
;                   for (int u = 0; u < 8; ++u) { kx[u] = *(const f32x4*)(p0 + u * 4096); vx[u] = *(const f32x4*)(p0 + u * 4096 + 256); }
.LBB0_2622:
	v_lshl_add_u64 v[80:81], s[14:15], 2, v[78:79]
	global_load_dwordx4 v[44:47], v[80:81], off offset:2048
	s_movk_i32 s0, 0x4000
	v_add_co_u32_e32 v82, vcc, s0, v80
	s_mov_b32 s0, 0x8000
	s_nop 0
	v_addc_co_u32_e32 v83, vcc, 0, v81, vcc
	global_load_dwordx4 v[12:15], v[82:83], off offset:2048
	v_add_co_u32_e32 v84, vcc, s0, v80
	s_mov_b32 s0, 0xc000
	s_nop 0
	v_addc_co_u32_e32 v85, vcc, 0, v81, vcc
	global_load_dwordx4 v[20:23], v[84:85], off offset:2048
	v_add_co_u32_e32 v86, vcc, s0, v80
	s_mov_b32 s0, 0x10000
	s_nop 0
	v_addc_co_u32_e32 v87, vcc, 0, v81, vcc
	global_load_dwordx4 v[24:27], v[86:87], off offset:2048
	v_add_co_u32_e32 v88, vcc, s0, v80
	s_mov_b32 s0, 0x14000
	s_nop 0
	v_addc_co_u32_e32 v89, vcc, 0, v81, vcc
	global_load_dwordx4 v[28:31], v[88:89], off offset:2048
	v_add_co_u32_e32 v90, vcc, s0, v80
	s_mov_b32 s0, 0x18000
	s_nop 0
	v_addc_co_u32_e32 v91, vcc, 0, v81, vcc
	global_load_dwordx4 v[32:35], v[90:91], off offset:2048
	v_add_co_u32_e32 v92, vcc, s0, v80
	s_mov_b32 s0, 0x1c000
	s_nop 0
	v_addc_co_u32_e32 v93, vcc, 0, v81, vcc
	global_load_dwordx4 v[36:39], v[92:93], off offset:2048
	v_add_co_u32_e32 v94, vcc, s0, v80
	s_waitcnt vmcnt(6)
	v_mov_b32_e32 v96, v45
	v_addc_co_u32_e32 v95, vcc, 0, v81, vcc
	global_load_dwordx4 v[40:43], v[94:95], off offset:2048
	global_load_dwordx4 v[150:153], v[80:81], off offset:3072
	global_load_dwordx4 v[154:157], v[82:83], off offset:3072
	global_load_dwordx4 v[158:161], v[84:85], off offset:3072
	global_load_dwordx4 v[162:165], v[86:87], off offset:3072
	global_load_dwordx4 v[166:169], v[88:89], off offset:3072
	global_load_dwordx4 v[170:173], v[90:91], off offset:3072
	global_load_dwordx4 v[174:177], v[92:93], off offset:3072
	global_load_dwordx4 v[178:181], v[94:95], off offset:3072
	v_mov_b32_e32 v45, v47
	v_mov_b32_e32 v97, v46
	v_pk_mul_f32 v[46:47], v[2:3], v[44:45]
	v_pk_mul_f32 v[126:127], v[6:7], v[44:45]
	v_pk_fma_f32 v[46:47], v[8:9], v[96:97], v[46:47]
	v_pk_fma_f32 v[126:127], v[54:55], v[96:97], v[126:127]
	v_add_f32_e32 v46, v46, v47
	s_waitcnt vmcnt(14)
	v_mov_b32_e32 v47, v14
	v_add_f32_dpp v46, v46, v46 quad_perm:[1,0,3,2] row_mask:0xf bank_mask:0xf bound_ctrl:1
	s_nop 1
	v_add_f32_dpp v46, v46, v46 quad_perm:[2,3,0,1] row_mask:0xf bank_mask:0xf bound_ctrl:1
	s_nop 1
	v_add_f32_dpp v46, v46, v46 row_half_mirror row_mask:0xf bank_mask:0xf bound_ctrl:1
	s_nop 1
	v_add_f32_dpp v118, v46, v46 row_mirror row_mask:0xf bank_mask:0xf bound_ctrl:1
	v_mov_b32_e32 v46, v13
	v_mov_b32_e32 v13, v15
	v_pk_mul_f32 v[14:15], v[2:3], v[12:13]
	v_pk_mul_f32 v[136:137], v[10:11], v[12:13]
	v_pk_fma_f32 v[14:15], v[8:9], v[46:47], v[14:15]
	v_pk_fma_f32 v[136:137], v[52:53], v[46:47], v[136:137]
	v_add_f32_e32 v14, v14, v15
	s_waitcnt vmcnt(13)
	v_mov_b32_e32 v15, v22
	v_add_f32_dpp v14, v14, v14 quad_perm:[1,0,3,2] row_mask:0xf bank_mask:0xf bound_ctrl:1
	s_nop 1
	v_add_f32_dpp v14, v14, v14 quad_perm:[2,3,0,1] row_mask:0xf bank_mask:0xf bound_ctrl:1
	s_nop 1
	v_add_f32_dpp v14, v14, v14 row_half_mirror row_mask:0xf bank_mask:0xf bound_ctrl:1
	s_nop 1
	v_add_f32_dpp v119, v14, v14 row_mirror row_mask:0xf bank_mask:0xf bound_ctrl:1
	v_mov_b32_e32 v14, v21
	v_mov_b32_e32 v21, v23
	v_pk_mul_f32 v[22:23], v[2:3], v[20:21]
	v_pk_mul_f32 v[128:129], v[6:7], v[20:21]
	v_pk_fma_f32 v[22:23], v[8:9], v[14:15], v[22:23]
	v_pk_fma_f32 v[128:129], v[54:55], v[14:15], v[128:129]
	v_add_f32_e32 v22, v22, v23
	s_waitcnt vmcnt(12)
	v_mov_b32_e32 v23, v26
	v_add_f32_dpp v22, v22, v22 quad_perm:[1,0,3,2] row_mask:0xf bank_mask:0xf bound_ctrl:1
	s_nop 1
	v_add_f32_dpp v22, v22, v22 quad_perm:[2,3,0,1] row_mask:0xf bank_mask:0xf bound_ctrl:1
	s_nop 1
	v_add_f32_dpp v22, v22, v22 row_half_mirror row_mask:0xf bank_mask:0xf bound_ctrl:1
	s_nop 1
	v_add_f32_dpp v120, v22, v22 row_mirror row_mask:0xf bank_mask:0xf bound_ctrl:1
	v_mov_b32_e32 v22, v25
	v_mov_b32_e32 v25, v27
	v_pk_mul_f32 v[26:27], v[2:3], v[24:25]
	v_pk_mul_f32 v[138:139], v[10:11], v[24:25]
	v_pk_fma_f32 v[26:27], v[8:9], v[22:23], v[26:27]
	v_pk_fma_f32 v[138:139], v[52:53], v[22:23], v[138:139]
	v_add_f32_e32 v26, v26, v27
	s_waitcnt vmcnt(11)
	v_mov_b32_e32 v27, v30
	v_add_f32_dpp v26, v26, v26 quad_perm:[1,0,3,2] row_mask:0xf bank_mask:0xf bound_ctrl:1
	s_nop 1
	v_add_f32_dpp v26, v26, v26 quad_perm:[2,3,0,1] row_mask:0xf bank_mask:0xf bound_ctrl:1
	s_nop 1
	v_add_f32_dpp v26, v26, v26 row_half_mirror row_mask:0xf bank_mask:0xf bound_ctrl:1
	s_nop 1
	v_add_f32_dpp v121, v26, v26 row_mirror row_mask:0xf bank_mask:0xf bound_ctrl:1
	v_mov_b32_e32 v26, v29
	v_mov_b32_e32 v29, v31
	v_pk_mul_f32 v[30:31], v[2:3], v[28:29]
	v_pk_mul_f32 v[130:131], v[6:7], v[28:29]
	v_pk_fma_f32 v[30:31], v[8:9], v[26:27], v[30:31]
	v_pk_fma_f32 v[130:131], v[54:55], v[26:27], v[130:131]
	v_add_f32_e32 v30, v30, v31
	s_waitcnt vmcnt(10)
	v_mov_b32_e32 v31, v34
	v_add_f32_dpp v30, v30, v30 quad_perm:[1,0,3,2] row_mask:0xf bank_mask:0xf bound_ctrl:1
	s_nop 1
	v_add_f32_dpp v30, v30, v30 quad_perm:[2,3,0,1] row_mask:0xf bank_mask:0xf bound_ctrl:1
	s_nop 1
	v_add_f32_dpp v30, v30, v30 row_half_mirror row_mask:0xf bank_mask:0xf bound_ctrl:1
	s_nop 1
	v_add_f32_dpp v122, v30, v30 row_mirror row_mask:0xf bank_mask:0xf bound_ctrl:1
	v_mov_b32_e32 v30, v33
	v_mov_b32_e32 v33, v35
	v_pk_mul_f32 v[34:35], v[2:3], v[32:33]
	v_pk_mul_f32 v[140:141], v[10:11], v[32:33]
	v_pk_fma_f32 v[34:35], v[8:9], v[30:31], v[34:35]
	v_pk_fma_f32 v[140:141], v[52:53], v[30:31], v[140:141]
	v_add_f32_e32 v34, v34, v35
	s_waitcnt vmcnt(9)
; __device__ __forceinline__ float max3f(float a, float b, float c) { float r; asm("v_max3_f32 %0, %1, %2, %3" : "=v"(r) : "v"(a), "v"(b), "v"(c)); return r; }
; __device__ __forceinline__ float dot4(f32x4 a, f32x4 b) { return (a[0] * b[0] + a[1] * b[1]) + (a[2] * b[2] + a[3] * b[3]); }
; __device__ __forceinline__ float grp16_sum(float v) { return sum16(v); }
; __device__ __forceinline__ void smp_batch(const f32x4 (&kx)[8], const f32x4 (&vx)[8], const f32x4 (&qv)[4], float (&m)[4], float (&l)[4], f32x4 (&o)[4]) {
; #pragma unroll
;     for (int h = 0; h < 4; ++h) { float s[8];
; #pragma unroll
;         for (int u = 0; u < 8; ++u) s[u] = grp16_sum(dot4(kx[u], qv[h]));
;         const float bm = fmaxf(max3f(max3f(s[0], s[1], s[2]), max3f(s[3], s[4], s[5]), s[6]), s[7]);
;         const bool mv = bm > m[h] + 8.0f;
;         if (__any(mv)) { const float mn = mv ? bm : m[h]; const float al = __builtin_amdgcn_exp2f(m[h] - mn); l[h] *= al; o[h] = o[h] * al; m[h] = mn; }
	v_mov_b32_e32 v35, v38
	v_add_f32_dpp v34, v34, v34 quad_perm:[1,0,3,2] row_mask:0xf bank_mask:0xf bound_ctrl:1
	s_nop 1
	v_add_f32_dpp v34, v34, v34 quad_perm:[2,3,0,1] row_mask:0xf bank_mask:0xf bound_ctrl:1
	s_nop 1
	v_add_f32_dpp v34, v34, v34 row_half_mirror row_mask:0xf bank_mask:0xf bound_ctrl:1
	s_nop 1
	v_add_f32_dpp v123, v34, v34 row_mirror row_mask:0xf bank_mask:0xf bound_ctrl:1
	v_mov_b32_e32 v34, v37
	v_mov_b32_e32 v37, v39
	v_pk_mul_f32 v[38:39], v[2:3], v[36:37]
	v_max3_f32 v125, v121, v122, v123
	v_pk_mul_f32 v[132:133], v[6:7], v[36:37]
	v_pk_fma_f32 v[38:39], v[8:9], v[34:35], v[38:39]
	v_pk_fma_f32 v[132:133], v[54:55], v[34:35], v[132:133]
	v_add_f32_e32 v38, v38, v39
	s_waitcnt vmcnt(8)
	v_mov_b32_e32 v39, v42
	v_add_f32_dpp v38, v38, v38 quad_perm:[1,0,3,2] row_mask:0xf bank_mask:0xf bound_ctrl:1
	s_nop 1
	v_add_f32_dpp v38, v38, v38 quad_perm:[2,3,0,1] row_mask:0xf bank_mask:0xf bound_ctrl:1
	s_nop 1
	v_add_f32_dpp v38, v38, v38 row_half_mirror row_mask:0xf bank_mask:0xf bound_ctrl:1
	s_nop 1
	v_add_f32_dpp v124, v38, v38 row_mirror row_mask:0xf bank_mask:0xf bound_ctrl:1
	v_mov_b32_e32 v38, v41
	v_mov_b32_e32 v41, v43
	v_pk_mul_f32 v[42:43], v[2:3], v[40:41]
	v_pk_mul_f32 v[142:143], v[10:11], v[40:41]
	v_pk_fma_f32 v[42:43], v[8:9], v[38:39], v[42:43]
	v_pk_fma_f32 v[142:143], v[52:53], v[38:39], v[142:143]
	v_add_f32_e32 v42, v42, v43
	v_max3_f32 v43, v118, v119, v120
	s_nop 0
	v_max3_f32 v43, v43, v125, v124
	v_add_f32_e32 v125, 0x41000000, v116
	v_add_f32_dpp v42, v42, v42 quad_perm:[1,0,3,2] row_mask:0xf bank_mask:0xf bound_ctrl:1
	v_max_f32_e32 v43, v43, v43
	s_nop 0
	v_add_f32_dpp v42, v42, v42 quad_perm:[2,3,0,1] row_mask:0xf bank_mask:0xf bound_ctrl:1
	s_nop 1
	v_add_f32_dpp v42, v42, v42 row_half_mirror row_mask:0xf bank_mask:0xf bound_ctrl:1
	s_nop 1
	v_add_f32_dpp v42, v42, v42 row_mirror row_mask:0xf bank_mask:0xf bound_ctrl:1
	v_max_f32_e32 v43, v43, v42
	v_cmp_gt_f32_e64 s[14:15], v43, v125
	v_add_f32_e32 v125, v126, v127
	v_pk_mul_f32 v[126:127], v[6:7], v[12:13]
	v_pk_mul_f32 v[12:13], v[18:19], v[12:13]
	v_pk_fma_f32 v[126:127], v[54:55], v[46:47], v[126:127]
	v_add_f32_dpp v125, v125, v125 quad_perm:[1,0,3,2] row_mask:0xf bank_mask:0xf bound_ctrl:1
	v_add_f32_e32 v126, v126, v127
	v_add_f32_e32 v127, v128, v129
	v_pk_mul_f32 v[128:129], v[6:7], v[24:25]
	v_add_f32_dpp v126, v126, v126 quad_perm:[1,0,3,2] row_mask:0xf bank_mask:0xf bound_ctrl:1
	v_pk_fma_f32 v[128:129], v[54:55], v[22:23], v[128:129]
	v_add_f32_dpp v127, v127, v127 quad_perm:[1,0,3,2] row_mask:0xf bank_mask:0xf bound_ctrl:1
	v_add_f32_e32 v128, v128, v129
	v_add_f32_e32 v129, v130, v131
	v_pk_mul_f32 v[130:131], v[6:7], v[32:33]
	v_add_f32_dpp v125, v125, v125 quad_perm:[2,3,0,1] row_mask:0xf bank_mask:0xf bound_ctrl:1
	v_pk_fma_f32 v[130:131], v[54:55], v[30:31], v[130:131]
	v_add_f32_dpp v126, v126, v126 quad_perm:[2,3,0,1] row_mask:0xf bank_mask:0xf bound_ctrl:1
	v_add_f32_e32 v130, v130, v131
	v_add_f32_e32 v131, v132, v133
	v_pk_mul_f32 v[132:133], v[6:7], v[40:41]
	v_add_f32_dpp v127, v127, v127 quad_perm:[2,3,0,1] row_mask:0xf bank_mask:0xf bound_ctrl:1
	v_pk_fma_f32 v[132:133], v[54:55], v[38:39], v[132:133]
	v_add_f32_dpp v128, v128, v128 quad_perm:[1,0,3,2] row_mask:0xf bank_mask:0xf bound_ctrl:1
	v_add_f32_dpp v129, v129, v129 quad_perm:[1,0,3,2] row_mask:0xf bank_mask:0xf bound_ctrl:1
	v_add_f32_dpp v130, v130, v130 quad_perm:[1,0,3,2] row_mask:0xf bank_mask:0xf bound_ctrl:1
	v_add_f32_dpp v131, v131, v131 quad_perm:[1,0,3,2] row_mask:0xf bank_mask:0xf bound_ctrl:1
	v_add_f32_e32 v132, v132, v133
	v_add_f32_dpp v125, v125, v125 row_half_mirror row_mask:0xf bank_mask:0xf bound_ctrl:1
	v_add_f32_dpp v126, v126, v126 row_half_mirror row_mask:0xf bank_mask:0xf bound_ctrl:1
	v_add_f32_dpp v127, v127, v127 row_half_mirror row_mask:0xf bank_mask:0xf bound_ctrl:1
	v_add_f32_dpp v128, v128, v128 quad_perm:[2,3,0,1] row_mask:0xf bank_mask:0xf bound_ctrl:1
	v_add_f32_dpp v129, v129, v129 quad_perm:[2,3,0,1] row_mask:0xf bank_mask:0xf bound_ctrl:1
	v_add_f32_dpp v130, v130, v130 quad_perm:[2,3,0,1] row_mask:0xf bank_mask:0xf bound_ctrl:1
	v_add_f32_dpp v131, v131, v131 quad_perm:[2,3,0,1] row_mask:0xf bank_mask:0xf bound_ctrl:1
	v_add_f32_dpp v132, v132, v132 quad_perm:[1,0,3,2] row_mask:0xf bank_mask:0xf bound_ctrl:1
	v_add_f32_dpp v125, v125, v125 row_mirror row_mask:0xf bank_mask:0xf bound_ctrl:1
	v_add_f32_dpp v126, v126, v126 row_mirror row_mask:0xf bank_mask:0xf bound_ctrl:1
	v_add_f32_dpp v127, v127, v127 row_mirror row_mask:0xf bank_mask:0xf bound_ctrl:1
	v_add_f32_dpp v128, v128, v128 row_half_mirror row_mask:0xf bank_mask:0xf bound_ctrl:1
	v_add_f32_dpp v129, v129, v129 row_half_mirror row_mask:0xf bank_mask:0xf bound_ctrl:1
	v_add_f32_dpp v130, v130, v130 row_half_mirror row_mask:0xf bank_mask:0xf bound_ctrl:1
	v_add_f32_dpp v131, v131, v131 row_half_mirror row_mask:0xf bank_mask:0xf bound_ctrl:1
	v_add_f32_dpp v132, v132, v132 quad_perm:[2,3,0,1] row_mask:0xf bank_mask:0xf bound_ctrl:1
	v_max3_f32 v133, v125, v126, v127
	v_add_f32_dpp v128, v128, v128 row_mirror row_mask:0xf bank_mask:0xf bound_ctrl:1
	v_add_f32_dpp v129, v129, v129 row_mirror row_mask:0xf bank_mask:0xf bound_ctrl:1
	v_add_f32_dpp v130, v130, v130 row_mirror row_mask:0xf bank_mask:0xf bound_ctrl:1
	v_add_f32_dpp v131, v131, v131 row_mirror row_mask:0xf bank_mask:0xf bound_ctrl:1
	v_add_f32_dpp v132, v132, v132 row_half_mirror row_mask:0xf bank_mask:0xf bound_ctrl:1
	v_max3_f32 v134, v128, v129, v130
	v_pk_fma_f32 v[12:13], v[50:51], v[46:47], v[12:13]
	v_max3_f32 v133, v133, v134, v131
	v_add_f32_e32 v134, 0x41000000, v114
; __device__ __forceinline__ float max3f(float a, float b, float c) { float r; asm("v_max3_f32 %0, %1, %2, %3" : "=v"(r) : "v"(a), "v"(b), "v"(c)); return r; }
; __device__ __forceinline__ float dot4(f32x4 a, f32x4 b) { return (a[0] * b[0] + a[1] * b[1]) + (a[2] * b[2] + a[3] * b[3]); }
; __device__ __forceinline__ float grp16_sum(float v) { return sum16(v); }
; __device__ __forceinline__ void smp_batch(const f32x4 (&kx)[8], const f32x4 (&vx)[8], const f32x4 (&qv)[4], float (&m)[4], float (&l)[4], f32x4 (&o)[4]) {
; #pragma unroll
;     for (int h = 0; h < 4; ++h) { float s[8];
; #pragma unroll
;         for (int u = 0; u < 8; ++u) s[u] = grp16_sum(dot4(kx[u], qv[h]));
;         const float bm = fmaxf(max3f(max3f(s[0], s[1], s[2]), max3f(s[3], s[4], s[5]), s[6]), s[7]);
;         const bool mv = bm > m[h] + 8.0f;
;         if (__any(mv)) { const float mn = mv ? bm : m[h]; const float al = __builtin_amdgcn_exp2f(m[h] - mn); l[h] *= al; o[h] = o[h] * al; m[h] = mn; }
	v_add_f32_dpp v132, v132, v132 row_mirror row_mask:0xf bank_mask:0xf bound_ctrl:1
	v_max_f32_e32 v133, v133, v133
	v_max_f32_e32 v133, v133, v132
	v_cmp_gt_f32_e64 s[18:19], v133, v134
	v_pk_mul_f32 v[134:135], v[10:11], v[44:45]
	v_add_f32_e32 v12, v12, v13
	v_pk_fma_f32 v[134:135], v[52:53], v[96:97], v[134:135]
	v_pk_mul_f32 v[44:45], v[18:19], v[44:45]
	v_add_f32_e32 v134, v134, v135
	v_add_f32_e32 v135, v136, v137
	v_pk_mul_f32 v[136:137], v[10:11], v[20:21]
	v_add_f32_dpp v12, v12, v12 quad_perm:[1,0,3,2] row_mask:0xf bank_mask:0xf bound_ctrl:1
	v_pk_fma_f32 v[136:137], v[52:53], v[14:15], v[136:137]
	v_add_f32_dpp v134, v134, v134 quad_perm:[1,0,3,2] row_mask:0xf bank_mask:0xf bound_ctrl:1
	v_add_f32_e32 v136, v136, v137
	v_add_f32_e32 v137, v138, v139
	v_pk_mul_f32 v[138:139], v[10:11], v[28:29]
	v_add_f32_dpp v12, v12, v12 quad_perm:[2,3,0,1] row_mask:0xf bank_mask:0xf bound_ctrl:1
	v_pk_fma_f32 v[138:139], v[52:53], v[26:27], v[138:139]
	v_add_f32_dpp v135, v135, v135 quad_perm:[1,0,3,2] row_mask:0xf bank_mask:0xf bound_ctrl:1
	v_add_f32_e32 v138, v138, v139
	v_add_f32_e32 v139, v140, v141
	v_pk_mul_f32 v[140:141], v[10:11], v[36:37]
	v_add_f32_dpp v136, v136, v136 quad_perm:[1,0,3,2] row_mask:0xf bank_mask:0xf bound_ctrl:1
	v_pk_fma_f32 v[140:141], v[52:53], v[34:35], v[140:141]
	v_add_f32_dpp v12, v12, v12 row_half_mirror row_mask:0xf bank_mask:0xf bound_ctrl:1
	v_add_f32_e32 v140, v140, v141
	v_add_f32_dpp v134, v134, v134 quad_perm:[2,3,0,1] row_mask:0xf bank_mask:0xf bound_ctrl:1
	v_add_f32_dpp v135, v135, v135 quad_perm:[2,3,0,1] row_mask:0xf bank_mask:0xf bound_ctrl:1
	v_add_f32_dpp v136, v136, v136 quad_perm:[2,3,0,1] row_mask:0xf bank_mask:0xf bound_ctrl:1
	v_add_f32_dpp v137, v137, v137 quad_perm:[1,0,3,2] row_mask:0xf bank_mask:0xf bound_ctrl:1
	v_add_f32_dpp v138, v138, v138 quad_perm:[1,0,3,2] row_mask:0xf bank_mask:0xf bound_ctrl:1
	v_add_f32_dpp v139, v139, v139 quad_perm:[1,0,3,2] row_mask:0xf bank_mask:0xf bound_ctrl:1
	v_add_f32_dpp v140, v140, v140 quad_perm:[1,0,3,2] row_mask:0xf bank_mask:0xf bound_ctrl:1
	v_add_f32_e32 v141, v142, v143
	v_pk_fma_f32 v[44:45], v[50:51], v[96:97], v[44:45]
	v_add_f32_dpp v97, v12, v12 row_mirror row_mask:0xf bank_mask:0xf bound_ctrl:1
	v_pk_mul_f32 v[12:13], v[18:19], v[20:21]
	v_add_f32_dpp v134, v134, v134 row_half_mirror row_mask:0xf bank_mask:0xf bound_ctrl:1
	v_add_f32_dpp v135, v135, v135 row_half_mirror row_mask:0xf bank_mask:0xf bound_ctrl:1
	v_add_f32_dpp v136, v136, v136 row_half_mirror row_mask:0xf bank_mask:0xf bound_ctrl:1
	v_add_f32_dpp v137, v137, v137 quad_perm:[2,3,0,1] row_mask:0xf bank_mask:0xf bound_ctrl:1
	v_add_f32_dpp v138, v138, v138 quad_perm:[2,3,0,1] row_mask:0xf bank_mask:0xf bound_ctrl:1
	v_add_f32_dpp v139, v139, v139 quad_perm:[2,3,0,1] row_mask:0xf bank_mask:0xf bound_ctrl:1
	v_add_f32_dpp v140, v140, v140 quad_perm:[2,3,0,1] row_mask:0xf bank_mask:0xf bound_ctrl:1
	v_add_f32_dpp v141, v141, v141 quad_perm:[1,0,3,2] row_mask:0xf bank_mask:0xf bound_ctrl:1
	v_pk_fma_f32 v[12:13], v[50:51], v[14:15], v[12:13]
	v_add_f32_dpp v134, v134, v134 row_mirror row_mask:0xf bank_mask:0xf bound_ctrl:1
	v_add_f32_dpp v135, v135, v135 row_mirror row_mask:0xf bank_mask:0xf bound_ctrl:1
	v_add_f32_dpp v136, v136, v136 row_mirror row_mask:0xf bank_mask:0xf bound_ctrl:1
	v_add_f32_dpp v137, v137, v137 row_half_mirror row_mask:0xf bank_mask:0xf bound_ctrl:1
	v_add_f32_dpp v138, v138, v138 row_half_mirror row_mask:0xf bank_mask:0xf bound_ctrl:1
	v_add_f32_dpp v139, v139, v139 row_half_mirror row_mask:0xf bank_mask:0xf bound_ctrl:1
	v_add_f32_dpp v140, v140, v140 row_half_mirror row_mask:0xf bank_mask:0xf bound_ctrl:1
	v_add_f32_dpp v141, v141, v141 quad_perm:[2,3,0,1] row_mask:0xf bank_mask:0xf bound_ctrl:1
	v_max3_f32 v142, v134, v135, v136
	v_add_f32_e32 v12, v12, v13
	v_add_f32_dpp v137, v137, v137 row_mirror row_mask:0xf bank_mask:0xf bound_ctrl:1
	v_add_f32_dpp v138, v138, v138 row_mirror row_mask:0xf bank_mask:0xf bound_ctrl:1
	v_add_f32_dpp v139, v139, v139 row_mirror row_mask:0xf bank_mask:0xf bound_ctrl:1
	v_add_f32_dpp v140, v140, v140 row_mirror row_mask:0xf bank_mask:0xf bound_ctrl:1
	v_add_f32_dpp v141, v141, v141 row_half_mirror row_mask:0xf bank_mask:0xf bound_ctrl:1
	v_max3_f32 v143, v137, v138, v139
	v_add_f32_dpp v12, v12, v12 quad_perm:[1,0,3,2] row_mask:0xf bank_mask:0xf bound_ctrl:1
	v_max3_f32 v142, v142, v143, v140
	v_add_f32_e32 v143, 0x41000000, v112
	v_add_f32_dpp v141, v141, v141 row_mirror row_mask:0xf bank_mask:0xf bound_ctrl:1
	v_max_f32_e32 v142, v142, v142
	v_add_f32_dpp v12, v12, v12 quad_perm:[2,3,0,1] row_mask:0xf bank_mask:0xf bound_ctrl:1
	v_max_f32_e32 v142, v142, v141
	v_cmp_gt_f32_e64 s[22:23], v142, v143
	v_add_f32_dpp v12, v12, v12 row_half_mirror row_mask:0xf bank_mask:0xf bound_ctrl:1
	v_add_f32_e32 v44, v44, v45
	s_cmp_eq_u64 s[14:15], 0
	v_add_f32_dpp v143, v12, v12 row_mirror row_mask:0xf bank_mask:0xf bound_ctrl:1
	v_pk_mul_f32 v[12:13], v[18:19], v[24:25]
	v_add_f32_dpp v44, v44, v44 quad_perm:[1,0,3,2] row_mask:0xf bank_mask:0xf bound_ctrl:1
	v_pk_fma_f32 v[12:13], v[50:51], v[22:23], v[12:13]
	s_cselect_b64 vcc, -1, 0
	v_add_f32_e32 v12, v12, v13
	v_add_f32_dpp v44, v44, v44 quad_perm:[2,3,0,1] row_mask:0xf bank_mask:0xf bound_ctrl:1
	s_cmp_eq_u64 s[18:19], 0
	v_add_f32_dpp v12, v12, v12 quad_perm:[1,0,3,2] row_mask:0xf bank_mask:0xf bound_ctrl:1
	v_add_f32_dpp v44, v44, v44 row_half_mirror row_mask:0xf bank_mask:0xf bound_ctrl:1
	s_cselect_b64 s[16:17], -1, 0
	v_add_f32_dpp v12, v12, v12 quad_perm:[2,3,0,1] row_mask:0xf bank_mask:0xf bound_ctrl:1
	v_add_f32_dpp v96, v44, v44 row_mirror row_mask:0xf bank_mask:0xf bound_ctrl:1
; __device__ __forceinline__ float max3f(float a, float b, float c) { float r; asm("v_max3_f32 %0, %1, %2, %3" : "=v"(r) : "v"(a), "v"(b), "v"(c)); return r; }
; __device__ __forceinline__ float dot4(f32x4 a, f32x4 b) { return (a[0] * b[0] + a[1] * b[1]) + (a[2] * b[2] + a[3] * b[3]); }
; __device__ __forceinline__ float grp16_sum(float v) { return sum16(v); }
; __device__ __forceinline__ void smp_batch(const f32x4 (&kx)[8], const f32x4 (&vx)[8], const f32x4 (&qv)[4], float (&m)[4], float (&l)[4], f32x4 (&o)[4]) {
; #pragma unroll
;     for (int h = 0; h < 4; ++h) { float s[8];
; #pragma unroll
;         for (int u = 0; u < 8; ++u) s[u] = grp16_sum(dot4(kx[u], qv[h]));
;         const float bm = fmaxf(max3f(max3f(s[0], s[1], s[2]), max3f(s[3], s[4], s[5]), s[6]), s[7]);
;         const bool mv = bm > m[h] + 8.0f;
;         if (__any(mv)) { const float mn = mv ? bm : m[h]; const float al = __builtin_amdgcn_exp2f(m[h] - mn); l[h] *= al; o[h] = o[h] * al; m[h] = mn; }
; #pragma unroll
;         for (int u = 0; u < 8; ++u) { const float p = __builtin_amdgcn_exp2f(s[u] - m[h]); l[h] += p; o[h] = o[h] + vx[u] * p; } }
	s_cmp_eq_u64 s[22:23], 0
	v_add_f32_dpp v12, v12, v12 row_half_mirror row_mask:0xf bank_mask:0xf bound_ctrl:1
	s_cselect_b64 s[20:21], -1, 0
	s_nop 0
	v_add_f32_dpp v144, v12, v12 row_mirror row_mask:0xf bank_mask:0xf bound_ctrl:1
	v_pk_mul_f32 v[12:13], v[18:19], v[28:29]
	s_nop 0
	v_pk_fma_f32 v[12:13], v[50:51], v[26:27], v[12:13]
	s_nop 0
	v_add_f32_e32 v12, v12, v13
	s_nop 1
	v_add_f32_dpp v12, v12, v12 quad_perm:[1,0,3,2] row_mask:0xf bank_mask:0xf bound_ctrl:1
	s_nop 1
	v_add_f32_dpp v12, v12, v12 quad_perm:[2,3,0,1] row_mask:0xf bank_mask:0xf bound_ctrl:1
	s_nop 1
	v_add_f32_dpp v12, v12, v12 row_half_mirror row_mask:0xf bank_mask:0xf bound_ctrl:1
	s_nop 1
	v_add_f32_dpp v145, v12, v12 row_mirror row_mask:0xf bank_mask:0xf bound_ctrl:1
	v_pk_mul_f32 v[12:13], v[18:19], v[32:33]
	s_nop 0
	v_pk_fma_f32 v[12:13], v[50:51], v[30:31], v[12:13]
	s_nop 0
	v_add_f32_e32 v12, v12, v13
	s_nop 1
	v_add_f32_dpp v12, v12, v12 quad_perm:[1,0,3,2] row_mask:0xf bank_mask:0xf bound_ctrl:1
	s_nop 1
	v_add_f32_dpp v12, v12, v12 quad_perm:[2,3,0,1] row_mask:0xf bank_mask:0xf bound_ctrl:1
	s_nop 1
	v_add_f32_dpp v12, v12, v12 row_half_mirror row_mask:0xf bank_mask:0xf bound_ctrl:1
	s_nop 1
	v_add_f32_dpp v146, v12, v12 row_mirror row_mask:0xf bank_mask:0xf bound_ctrl:1
	v_pk_mul_f32 v[12:13], v[18:19], v[36:37]
	s_nop 0
	v_pk_fma_f32 v[12:13], v[50:51], v[34:35], v[12:13]
	s_nop 0
	v_add_f32_e32 v12, v12, v13
	s_nop 1
	v_add_f32_dpp v12, v12, v12 quad_perm:[1,0,3,2] row_mask:0xf bank_mask:0xf bound_ctrl:1
	s_nop 1
	v_add_f32_dpp v12, v12, v12 quad_perm:[2,3,0,1] row_mask:0xf bank_mask:0xf bound_ctrl:1
	s_nop 1
	v_add_f32_dpp v12, v12, v12 row_half_mirror row_mask:0xf bank_mask:0xf bound_ctrl:1
	s_nop 1
	v_add_f32_dpp v147, v12, v12 row_mirror row_mask:0xf bank_mask:0xf bound_ctrl:1
	v_pk_mul_f32 v[12:13], v[18:19], v[40:41]
	v_cndmask_b32_e64 v41, v116, v43, s[14:15]
	v_pk_fma_f32 v[12:13], v[50:51], v[38:39], v[12:13]
	v_sub_f32_e32 v40, v116, v41
	v_add_f32_e32 v12, v12, v13
	v_max3_f32 v13, v144, v145, v146
	v_exp_f32_e32 v40, v40
	v_cndmask_b32_e32 v116, v41, v116, vcc
	v_add_f32_dpp v12, v12, v12 quad_perm:[1,0,3,2] row_mask:0xf bank_mask:0xf bound_ctrl:1
	v_sub_f32_e32 v42, v42, v116
	v_exp_f32_e32 v42, v42
	v_add_f32_dpp v12, v12, v12 quad_perm:[2,3,0,1] row_mask:0xf bank_mask:0xf bound_ctrl:1
	s_mov_b64 s[14:15], 0x8000
	s_nop 0
	v_add_f32_dpp v12, v12, v12 row_half_mirror row_mask:0xf bank_mask:0xf bound_ctrl:1
	s_nop 1
	v_add_f32_dpp v148, v12, v12 row_mirror row_mask:0xf bank_mask:0xf bound_ctrl:1
	v_max3_f32 v12, v96, v97, v143
	s_nop 0
	v_max3_f32 v12, v12, v13, v147
	s_nop 0
	v_max_f32_e32 v12, v12, v12
	v_max_f32_e32 v149, v12, v148
	v_add_f32_e32 v12, 0x41000000, v110
	v_cmp_gt_f32_e64 s[26:27], v149, v12
	v_pk_mul_f32 v[84:85], v[64:65], v[40:41] op_sel_hi:[1,0]
	v_pk_mul_f32 v[86:87], v[76:77], v[40:41] op_sel_hi:[1,0]
	v_mul_f32_e32 v40, v117, v40
	v_cndmask_b32_e32 v43, v40, v117, vcc
	v_cndmask_b32_e32 v40, v86, v76, vcc
	v_sub_f32_e32 v76, v118, v116
	v_exp_f32_e32 v76, v76
	v_cndmask_b32_e32 v41, v87, v77, vcc
	v_cndmask_b32_e32 v65, v85, v65, vcc
	v_cndmask_b32_e32 v64, v84, v64, vcc
	v_add_f32_e32 v43, v76, v43
	s_cmp_eq_u64 s[26:27], 0
	s_cselect_b64 s[24:25], -1, 0
	s_andn2_b64 vcc, exec, s[92:93]
	s_mov_b64 s[92:93], 0
	s_waitcnt vmcnt(7)
	v_mov_b64 v[12:13], v[150:151]
	v_mov_b64 v[14:15], v[152:153]
	v_pk_fma_f32 v[64:65], v[12:13], v[76:77], v[64:65] op_sel_hi:[1,0,1]
	v_pk_fma_f32 v[40:41], v[14:15], v[76:77], v[40:41] op_sel_hi:[1,0,1]
	v_sub_f32_e32 v76, v119, v116
	v_exp_f32_e32 v76, v76
	s_nop 0
	v_add_f32_e32 v43, v76, v43
	s_waitcnt vmcnt(6)
	v_mov_b64 v[20:21], v[154:155]
	v_mov_b64 v[22:23], v[156:157]
	v_pk_fma_f32 v[40:41], v[22:23], v[76:77], v[40:41] op_sel_hi:[1,0,1]
	v_pk_fma_f32 v[64:65], v[20:21], v[76:77], v[64:65] op_sel_hi:[1,0,1]
	v_sub_f32_e32 v76, v120, v116
	v_exp_f32_e32 v76, v76
	s_nop 0
	v_add_f32_e32 v43, v76, v43
	s_waitcnt vmcnt(5)
	v_mov_b64 v[24:25], v[158:159]
	v_mov_b64 v[26:27], v[160:161]
	v_pk_fma_f32 v[64:65], v[24:25], v[76:77], v[64:65] op_sel_hi:[1,0,1]
	v_pk_fma_f32 v[40:41], v[26:27], v[76:77], v[40:41] op_sel_hi:[1,0,1]
	v_sub_f32_e32 v76, v121, v116
	v_exp_f32_e32 v76, v76
	s_nop 0
	v_add_f32_e32 v43, v76, v43
	s_waitcnt vmcnt(4)
	v_mov_b64 v[28:29], v[162:163]
	v_mov_b64 v[30:31], v[164:165]
	v_pk_fma_f32 v[40:41], v[30:31], v[76:77], v[40:41] op_sel_hi:[1,0,1]
	v_pk_fma_f32 v[64:65], v[28:29], v[76:77], v[64:65] op_sel_hi:[1,0,1]
	v_sub_f32_e32 v76, v122, v116
	v_exp_f32_e32 v76, v76
	s_nop 0
	v_add_f32_e32 v43, v76, v43
	s_waitcnt vmcnt(3)
	v_mov_b64 v[32:33], v[166:167]
	v_mov_b64 v[34:35], v[168:169]
	v_pk_fma_f32 v[64:65], v[32:33], v[76:77], v[64:65] op_sel_hi:[1,0,1]
	v_pk_fma_f32 v[40:41], v[34:35], v[76:77], v[40:41] op_sel_hi:[1,0,1]
	v_sub_f32_e32 v76, v123, v116
	v_exp_f32_e32 v76, v76
	s_nop 0
	v_add_f32_e32 v43, v76, v43
	s_waitcnt vmcnt(2)
	v_mov_b64 v[36:37], v[170:171]
	v_mov_b64 v[38:39], v[172:173]
	v_pk_fma_f32 v[40:41], v[38:39], v[76:77], v[40:41] op_sel_hi:[1,0,1]
	v_pk_fma_f32 v[64:65], v[36:37], v[76:77], v[64:65] op_sel_hi:[1,0,1]
	v_sub_f32_e32 v76, v124, v116
	v_exp_f32_e32 v76, v76
	s_nop 0
	v_add_f32_e32 v43, v76, v43
	s_waitcnt vmcnt(1)
	v_mov_b64 v[44:45], v[174:175]
	v_mov_b64 v[46:47], v[176:177]
	v_pk_fma_f32 v[40:41], v[46:47], v[76:77], v[40:41] op_sel_hi:[1,0,1]
	v_pk_fma_f32 v[64:65], v[44:45], v[76:77], v[64:65] op_sel_hi:[1,0,1]
	s_waitcnt vmcnt(0)
; __device__ __forceinline__ float max3f(float a, float b, float c) { float r; asm("v_max3_f32 %0, %1, %2, %3" : "=v"(r) : "v"(a), "v"(b), "v"(c)); return r; }
; __device__ __forceinline__ float dot4(f32x4 a, f32x4 b) { return (a[0] * b[0] + a[1] * b[1]) + (a[2] * b[2] + a[3] * b[3]); }
; __device__ __forceinline__ float grp16_sum(float v) { return sum16(v); }
; __device__ __forceinline__ void smp_batch(const f32x4 (&kx)[8], const f32x4 (&vx)[8], const f32x4 (&qv)[4], float (&m)[4], float (&l)[4], f32x4 (&o)[4]) {
; #pragma unroll
;     for (int h = 0; h < 4; ++h) { float s[8];
; #pragma unroll
;         for (int u = 0; u < 8; ++u) s[u] = grp16_sum(dot4(kx[u], qv[h]));
;         const float bm = fmaxf(max3f(max3f(s[0], s[1], s[2]), max3f(s[3], s[4], s[5]), s[6]), s[7]);
;         const bool mv = bm > m[h] + 8.0f;
;         if (__any(mv)) { const float mn = mv ? bm : m[h]; const float al = __builtin_amdgcn_exp2f(m[h] - mn); l[h] *= al; o[h] = o[h] * al; m[h] = mn; }
; #pragma unroll
;         for (int u = 0; u < 8; ++u) { const float p = __builtin_amdgcn_exp2f(s[u] - m[h]); l[h] += p; o[h] = o[h] + vx[u] * p; } }
; }
	v_mov_b64 v[80:81], v[178:179]
	v_mov_b64 v[82:83], v[180:181]
	v_pk_fma_f32 v[76:77], v[82:83], v[42:43], v[40:41] op_sel_hi:[1,0,1]
	v_cndmask_b32_e64 v41, v114, v133, s[18:19]
	v_sub_f32_e32 v40, v114, v41
	v_exp_f32_e32 v40, v40
	v_add_f32_e32 v117, v42, v43
	v_pk_fma_f32 v[64:65], v[80:81], v[42:43], v[64:65] op_sel_hi:[1,0,1]
	v_cndmask_b32_e64 v114, v41, v114, s[16:17]
	v_pk_mul_f32 v[42:43], v[68:69], v[40:41] op_sel_hi:[1,0]
	v_pk_mul_f32 v[84:85], v[66:67], v[40:41] op_sel_hi:[1,0]
	v_mul_f32_e32 v40, v115, v40
	v_cndmask_b32_e64 v86, v40, v115, s[16:17]
	v_cndmask_b32_e64 v40, v42, v68, s[16:17]
	v_cndmask_b32_e64 v42, v84, v66, s[16:17]
	v_sub_f32_e32 v66, v125, v114
	v_exp_f32_e32 v66, v66
	v_cndmask_b32_e64 v41, v43, v69, s[16:17]
	v_cndmask_b32_e64 v43, v85, v67, s[16:17]
	v_add_f32_e32 v67, v66, v86
	v_pk_fma_f32 v[42:43], v[12:13], v[66:67], v[42:43] op_sel_hi:[1,0,1]
	v_pk_fma_f32 v[40:41], v[14:15], v[66:67], v[40:41] op_sel_hi:[1,0,1]
	v_sub_f32_e32 v66, v126, v114
	v_exp_f32_e32 v66, v66
	s_nop 0
	v_add_f32_e32 v67, v66, v67
	v_pk_fma_f32 v[40:41], v[22:23], v[66:67], v[40:41] op_sel_hi:[1,0,1]
	v_pk_fma_f32 v[42:43], v[20:21], v[66:67], v[42:43] op_sel_hi:[1,0,1]
	v_sub_f32_e32 v66, v127, v114
	v_exp_f32_e32 v66, v66
	s_nop 0
	v_add_f32_e32 v67, v66, v67
	v_pk_fma_f32 v[42:43], v[24:25], v[66:67], v[42:43] op_sel_hi:[1,0,1]
	v_pk_fma_f32 v[40:41], v[26:27], v[66:67], v[40:41] op_sel_hi:[1,0,1]
	v_sub_f32_e32 v66, v128, v114
	v_exp_f32_e32 v66, v66
	s_nop 0
	v_add_f32_e32 v67, v66, v67
	v_pk_fma_f32 v[40:41], v[30:31], v[66:67], v[40:41] op_sel_hi:[1,0,1]
	v_pk_fma_f32 v[42:43], v[28:29], v[66:67], v[42:43] op_sel_hi:[1,0,1]
	v_sub_f32_e32 v66, v129, v114
	v_exp_f32_e32 v66, v66
	s_nop 0
	v_add_f32_e32 v67, v66, v67
	v_pk_fma_f32 v[42:43], v[32:33], v[66:67], v[42:43] op_sel_hi:[1,0,1]
	v_pk_fma_f32 v[40:41], v[34:35], v[66:67], v[40:41] op_sel_hi:[1,0,1]
	v_sub_f32_e32 v66, v130, v114
	v_exp_f32_e32 v66, v66
	s_nop 0
	v_add_f32_e32 v67, v66, v67
	v_pk_fma_f32 v[40:41], v[38:39], v[66:67], v[40:41] op_sel_hi:[1,0,1]
	v_pk_fma_f32 v[42:43], v[36:37], v[66:67], v[42:43] op_sel_hi:[1,0,1]
	v_sub_f32_e32 v66, v131, v114
	v_exp_f32_e32 v66, v66
	s_nop 0
	v_add_f32_e32 v67, v66, v67
	v_pk_fma_f32 v[42:43], v[44:45], v[66:67], v[42:43] op_sel_hi:[1,0,1]
	v_pk_fma_f32 v[40:41], v[46:47], v[66:67], v[40:41] op_sel_hi:[1,0,1]
	v_sub_f32_e32 v66, v132, v114
	v_exp_f32_e32 v66, v66
	s_nop 0
	v_pk_fma_f32 v[68:69], v[82:83], v[66:67], v[40:41] op_sel_hi:[1,0,1]
	v_cndmask_b32_e64 v41, v112, v142, s[22:23]
	v_sub_f32_e32 v40, v112, v41
	v_exp_f32_e32 v40, v40
	v_add_f32_e32 v115, v66, v67
	v_pk_fma_f32 v[66:67], v[80:81], v[66:67], v[42:43] op_sel_hi:[1,0,1]
	v_cndmask_b32_e64 v112, v41, v112, s[20:21]
	v_pk_mul_f32 v[42:43], v[62:63], v[40:41] op_sel_hi:[1,0]
	v_pk_mul_f32 v[84:85], v[60:61], v[40:41] op_sel_hi:[1,0]
	v_mul_f32_e32 v40, v113, v40
	v_cndmask_b32_e64 v86, v40, v113, s[20:21]
	v_cndmask_b32_e64 v40, v42, v62, s[20:21]
	v_cndmask_b32_e64 v42, v84, v60, s[20:21]
	v_sub_f32_e32 v60, v134, v112
	v_exp_f32_e32 v60, v60
	v_cndmask_b32_e64 v41, v43, v63, s[20:21]
	v_cndmask_b32_e64 v43, v85, v61, s[20:21]
	v_add_f32_e32 v61, v60, v86
	v_pk_fma_f32 v[42:43], v[12:13], v[60:61], v[42:43] op_sel_hi:[1,0,1]
	v_pk_fma_f32 v[40:41], v[14:15], v[60:61], v[40:41] op_sel_hi:[1,0,1]
	v_sub_f32_e32 v60, v135, v112
	v_exp_f32_e32 v60, v60
	s_nop 0
	v_add_f32_e32 v61, v60, v61
	v_pk_fma_f32 v[40:41], v[22:23], v[60:61], v[40:41] op_sel_hi:[1,0,1]
	v_pk_fma_f32 v[42:43], v[20:21], v[60:61], v[42:43] op_sel_hi:[1,0,1]
	v_sub_f32_e32 v60, v136, v112
	v_exp_f32_e32 v60, v60
	s_nop 0
	v_add_f32_e32 v61, v60, v61
	v_pk_fma_f32 v[42:43], v[24:25], v[60:61], v[42:43] op_sel_hi:[1,0,1]
; __device__ __forceinline__ float max3f(float a, float b, float c) { float r; asm("v_max3_f32 %0, %1, %2, %3" : "=v"(r) : "v"(a), "v"(b), "v"(c)); return r; }
; __device__ __forceinline__ int nth_bit(unsigned long long m, int n) { for (int x = 0; x < n; ++x) m &= m - 1ull; return __builtin_ctzll(m); }
; __device__ __forceinline__ float dot4(f32x4 a, f32x4 b) { return (a[0] * b[0] + a[1] * b[1]) + (a[2] * b[2] + a[3] * b[3]); }
; __device__ __forceinline__ float grp16_sum(float v) { return sum16(v); }
; __device__ __forceinline__ void smp_batch(const f32x4 (&kx)[8], const f32x4 (&vx)[8], const f32x4 (&qv)[4], float (&m)[4], float (&l)[4], f32x4 (&o)[4]) {
; #pragma unroll
;     for (int h = 0; h < 4; ++h) { float s[8];
; #pragma unroll
;         for (int u = 0; u < 8; ++u) s[u] = grp16_sum(dot4(kx[u], qv[h]));
;         const float bm = fmaxf(max3f(max3f(s[0], s[1], s[2]), max3f(s[3], s[4], s[5]), s[6]), s[7]);
;         const bool mv = bm > m[h] + 8.0f;
;         if (__any(mv)) { const float mn = mv ? bm : m[h]; const float al = __builtin_amdgcn_exp2f(m[h] - mn); l[h] *= al; o[h] = o[h] * al; m[h] = mn; }
; #pragma unroll
;         for (int u = 0; u < 8; ++u) { const float p = __builtin_amdgcn_exp2f(s[u] - m[h]); l[h] += p; o[h] = o[h] + vx[u] * p; } }
; }
; __device__ __forceinline__ void attn_sample_item(const SmpArgs& a, int b, int g, LAS unsigned char* lds, int tid) {
;     ...
;       for (int bi = 0; bi < 2; ++bi) { const int j = nth_bit(mask, 2 * w + bi);
;           if (j < 32) { const int phys = a.page_table[b * 16 + (j >> 1)];
;               const float* base = a.cache_kv + ((size_t)phys * 128 + (j & 1) * 64 + kq) * 1024 + 512 + g * 64 + 4 * d4;
; #pragma unroll 1
;               for (int it8 = 0; it8 < 2; ++it8) { const float* p0 = base + (size_t)it8 * 32 * 1024; f32x4 kx[8], vx[8];
; #pragma unroll
;                   for (int u = 0; u < 8; ++u) { kx[u] = *(const f32x4*)(p0 + u * 4096); vx[u] = *(const f32x4*)(p0 + u * 4096 + 256); }
;                   smp_batch(kx, vx, qv, m, l, o); } }
	v_pk_fma_f32 v[40:41], v[26:27], v[60:61], v[40:41] op_sel_hi:[1,0,1]
	v_sub_f32_e32 v60, v137, v112
	v_exp_f32_e32 v60, v60
	s_nop 0
	v_add_f32_e32 v61, v60, v61
	v_pk_fma_f32 v[40:41], v[30:31], v[60:61], v[40:41] op_sel_hi:[1,0,1]
	v_pk_fma_f32 v[42:43], v[28:29], v[60:61], v[42:43] op_sel_hi:[1,0,1]
	v_sub_f32_e32 v60, v138, v112
	v_exp_f32_e32 v60, v60
	s_nop 0
	v_add_f32_e32 v61, v60, v61
	v_pk_fma_f32 v[42:43], v[32:33], v[60:61], v[42:43] op_sel_hi:[1,0,1]
	v_pk_fma_f32 v[40:41], v[34:35], v[60:61], v[40:41] op_sel_hi:[1,0,1]
	v_sub_f32_e32 v60, v139, v112
	v_exp_f32_e32 v60, v60
	s_nop 0
	v_add_f32_e32 v61, v60, v61
	v_pk_fma_f32 v[40:41], v[38:39], v[60:61], v[40:41] op_sel_hi:[1,0,1]
	v_pk_fma_f32 v[42:43], v[36:37], v[60:61], v[42:43] op_sel_hi:[1,0,1]
	v_sub_f32_e32 v60, v140, v112
	v_exp_f32_e32 v60, v60
	s_nop 0
	v_add_f32_e32 v61, v60, v61
	v_pk_fma_f32 v[42:43], v[44:45], v[60:61], v[42:43] op_sel_hi:[1,0,1]
	v_pk_fma_f32 v[40:41], v[46:47], v[60:61], v[40:41] op_sel_hi:[1,0,1]
	v_sub_f32_e32 v60, v141, v112
	v_exp_f32_e32 v60, v60
	s_nop 0
	v_pk_fma_f32 v[62:63], v[82:83], v[60:61], v[40:41] op_sel_hi:[1,0,1]
	v_cndmask_b32_e64 v41, v110, v149, s[26:27]
	v_sub_f32_e32 v40, v110, v41
	v_exp_f32_e32 v40, v40
	v_add_f32_e32 v113, v60, v61
	v_pk_fma_f32 v[60:61], v[80:81], v[60:61], v[42:43] op_sel_hi:[1,0,1]
	v_cndmask_b32_e64 v110, v41, v110, s[24:25]
	v_pk_mul_f32 v[42:43], v[58:59], v[40:41] op_sel_hi:[1,0]
	v_pk_mul_f32 v[84:85], v[4:5], v[40:41] op_sel_hi:[1,0]
	v_mul_f32_e32 v40, v111, v40
	v_cndmask_b32_e64 v86, v40, v111, s[24:25]
	v_cndmask_b32_e64 v40, v42, v58, s[24:25]
	v_sub_f32_e32 v42, v96, v110
	v_exp_f32_e32 v42, v42
	v_cndmask_b32_e64 v41, v43, v59, s[24:25]
	v_cndmask_b32_e64 v5, v85, v5, s[24:25]
	v_cndmask_b32_e64 v4, v84, v4, s[24:25]
	v_add_f32_e32 v43, v42, v86
	v_pk_fma_f32 v[4:5], v[12:13], v[42:43], v[4:5] op_sel_hi:[1,0,1]
	v_pk_fma_f32 v[12:13], v[14:15], v[42:43], v[40:41] op_sel_hi:[1,0,1]
	v_sub_f32_e32 v14, v97, v110
	v_exp_f32_e32 v14, v14
	s_nop 0
	v_add_f32_e32 v15, v14, v43
	v_pk_fma_f32 v[12:13], v[22:23], v[14:15], v[12:13] op_sel_hi:[1,0,1]
	v_pk_fma_f32 v[4:5], v[20:21], v[14:15], v[4:5] op_sel_hi:[1,0,1]
	v_sub_f32_e32 v14, v143, v110
	v_exp_f32_e32 v14, v14
	s_nop 0
	v_add_f32_e32 v15, v14, v15
	v_pk_fma_f32 v[4:5], v[24:25], v[14:15], v[4:5] op_sel_hi:[1,0,1]
	v_pk_fma_f32 v[12:13], v[26:27], v[14:15], v[12:13] op_sel_hi:[1,0,1]
	v_sub_f32_e32 v14, v144, v110
	v_exp_f32_e32 v14, v14
	s_nop 0
	v_add_f32_e32 v15, v14, v15
	v_pk_fma_f32 v[12:13], v[30:31], v[14:15], v[12:13] op_sel_hi:[1,0,1]
	v_pk_fma_f32 v[4:5], v[28:29], v[14:15], v[4:5] op_sel_hi:[1,0,1]
	v_sub_f32_e32 v14, v145, v110
	v_exp_f32_e32 v14, v14
	s_nop 0
	v_add_f32_e32 v15, v14, v15
	v_pk_fma_f32 v[4:5], v[32:33], v[14:15], v[4:5] op_sel_hi:[1,0,1]
	v_pk_fma_f32 v[12:13], v[34:35], v[14:15], v[12:13] op_sel_hi:[1,0,1]
	v_sub_f32_e32 v14, v146, v110
	v_exp_f32_e32 v14, v14
	s_nop 0
	v_add_f32_e32 v15, v14, v15
	v_pk_fma_f32 v[12:13], v[38:39], v[14:15], v[12:13] op_sel_hi:[1,0,1]
	v_pk_fma_f32 v[4:5], v[36:37], v[14:15], v[4:5] op_sel_hi:[1,0,1]
	v_sub_f32_e32 v14, v147, v110
	v_exp_f32_e32 v14, v14
	s_nop 0
	v_add_f32_e32 v15, v14, v15
	v_pk_fma_f32 v[4:5], v[44:45], v[14:15], v[4:5] op_sel_hi:[1,0,1]
	v_pk_fma_f32 v[12:13], v[46:47], v[14:15], v[12:13] op_sel_hi:[1,0,1]
	v_sub_f32_e32 v14, v148, v110
	v_exp_f32_e32 v14, v14
	s_nop 0
	v_add_f32_e32 v111, v14, v15
	v_pk_fma_f32 v[58:59], v[82:83], v[14:15], v[12:13] op_sel_hi:[1,0,1]
	v_pk_fma_f32 v[4:5], v[80:81], v[14:15], v[4:5] op_sel_hi:[1,0,1]
	s_cbranch_vccz .LBB0_2622
	v_mov_b32_e32 v31, v111
	v_mov_b32_e32 v28, v113
	v_mov_b32_e32 v27, v115
	v_mov_b32_e32 v22, v117
	v_mov_b32_e32 v23, v116
	v_mov_b32_e32 v29, v114
	v_mov_b32_e32 v30, v112
	v_mov_b32_e32 v25, v110

; __device__ __forceinline__ float max3f(float a, float b, float c) { float r; asm("v_max3_f32 %0, %1, %2, %3" : "=v"(r) : "v"(a), "v"(b), "v"(c)); return r; }
; __device__ __forceinline__ float dot4(f32x4 a, f32x4 b) { return (a[0] * b[0] + a[1] * b[1]) + (a[2] * b[2] + a[3] * b[3]); }
; __device__ __forceinline__ float grp16_sum(float v) { return sum16(v); }
; __device__ __forceinline__ void smp_batch(const f32x4 (&kx)[8], const f32x4 (&vx)[8], const f32x4 (&qv)[4], float (&m)[4], float (&l)[4], f32x4 (&o)[4]) {
; #pragma unroll
;     for (int h = 0; h < 4; ++h) { float s[8];
; #pragma unroll
;         for (int u = 0; u < 8; ++u) s[u] = grp16_sum(dot4(kx[u], qv[h]));
;         const float bm = fmaxf(max3f(max3f(s[0], s[1], s[2]), max3f(s[3], s[4], s[5]), s[6]), s[7]);
; __device__ __forceinline__ void attn_sample_item(const SmpArgs& a, int b, int g, LAS unsigned char* lds, int tid) {
;     ...
;       for (int it8 = 0; it8 < 2; ++it8) { f32x4 kx[8], vx[8];
; #pragma unroll
;           for (int u = 0; u < 8; ++u) { const int kk = 64 * w + 32 * it8 + 4 * u + kq;
;               const float* p0 = kk < 511 ? a.cache_win + (((size_t)b * 512 + kk + 1) * 2) * 256 + g * 64 + 4 * d4 : a.out + OFF_WINS + (size_t)b * 512 + g * 64 + 4 * d4;
;               kx[u] = *(const f32x4*)p0; vx[u] = *(const f32x4*)(p0 + 256); }
;           smp_batch(kx, vx, qv, m, l, o); }
.LBB0_2641:
	v_or_b32_e32 v44, s16, v96
	v_ashrrev_i32_e32 v45, 31, v44
	v_lshlrev_b64 v[12:13], 11, v[44:45]
	v_lshl_add_u64 v[12:13], s[88:89], 0, v[12:13]
	v_cmp_gt_i32_e32 vcc, s96, v44
	v_lshl_add_u64 v[12:13], v[12:13], 0, s[80:81]
	v_mov_b32_e32 v46, s1
	v_mov_b32_e32 v47, s0
	v_cndmask_b32_e32 v13, v46, v13, vcc
	v_cndmask_b32_e32 v12, v47, v12, vcc
	v_lshl_add_u64 v[76:77], v[12:13], 0, v[0:1]
	global_load_dwordx4 v[12:15], v[76:77], off
	v_or_b32_e32 v20, 4, v44
	v_ashrrev_i32_e32 v21, 31, v20
	v_cmp_gt_i32_e32 vcc, s96, v20
	v_lshlrev_b64 v[20:21], 11, v[20:21]
	v_lshl_add_u64 v[20:21], s[88:89], 0, v[20:21]
	v_lshl_add_u64 v[20:21], v[20:21], 0, s[80:81]
	v_cndmask_b32_e32 v21, v46, v21, vcc
	v_cndmask_b32_e32 v20, v47, v20, vcc
	v_lshl_add_u64 v[78:79], v[20:21], 0, v[0:1]
	global_load_dwordx4 v[20:23], v[78:79], off
	v_or_b32_e32 v24, 8, v44
	v_ashrrev_i32_e32 v25, 31, v24
	v_cmp_gt_i32_e32 vcc, s96, v24
	v_lshlrev_b64 v[24:25], 11, v[24:25]
	v_lshl_add_u64 v[24:25], s[88:89], 0, v[24:25]
	v_lshl_add_u64 v[24:25], v[24:25], 0, s[80:81]
	v_cndmask_b32_e32 v25, v46, v25, vcc
	v_cndmask_b32_e32 v24, v47, v24, vcc
	v_lshl_add_u64 v[80:81], v[24:25], 0, v[0:1]
	global_load_dwordx4 v[24:27], v[80:81], off
	v_or_b32_e32 v28, 12, v44
	v_ashrrev_i32_e32 v29, 31, v28
	v_cmp_gt_i32_e32 vcc, s96, v28
	v_lshlrev_b64 v[28:29], 11, v[28:29]
	v_lshl_add_u64 v[28:29], s[88:89], 0, v[28:29]
	v_lshl_add_u64 v[28:29], v[28:29], 0, s[80:81]
	v_cndmask_b32_e32 v29, v46, v29, vcc
	v_cndmask_b32_e32 v28, v47, v28, vcc
	v_lshl_add_u64 v[82:83], v[28:29], 0, v[0:1]
	global_load_dwordx4 v[28:31], v[82:83], off
	v_or_b32_e32 v32, 16, v44
	v_ashrrev_i32_e32 v33, 31, v32
	v_cmp_gt_i32_e32 vcc, s96, v32
	v_lshlrev_b64 v[32:33], 11, v[32:33]
	v_lshl_add_u64 v[32:33], s[88:89], 0, v[32:33]
	v_lshl_add_u64 v[32:33], v[32:33], 0, s[80:81]
	v_cndmask_b32_e32 v33, v46, v33, vcc
	v_cndmask_b32_e32 v32, v47, v32, vcc
	v_lshl_add_u64 v[84:85], v[32:33], 0, v[0:1]
	global_load_dwordx4 v[32:35], v[84:85], off
	v_or_b32_e32 v36, 20, v44
	v_ashrrev_i32_e32 v37, 31, v36
	v_cmp_gt_i32_e32 vcc, s96, v36
	v_lshlrev_b64 v[36:37], 11, v[36:37]
	v_lshl_add_u64 v[36:37], s[88:89], 0, v[36:37]
	v_lshl_add_u64 v[36:37], v[36:37], 0, s[80:81]
	v_cndmask_b32_e32 v37, v46, v37, vcc
	v_cndmask_b32_e32 v36, v47, v36, vcc
	v_lshl_add_u64 v[86:87], v[36:37], 0, v[0:1]
	global_load_dwordx4 v[36:39], v[86:87], off
	v_or_b32_e32 v40, 24, v44
	v_ashrrev_i32_e32 v41, 31, v40
	v_cmp_gt_i32_e32 vcc, s96, v40
	v_lshlrev_b64 v[40:41], 11, v[40:41]
	v_lshl_add_u64 v[40:41], s[88:89], 0, v[40:41]
	v_lshl_add_u64 v[40:41], v[40:41], 0, s[80:81]
	v_cndmask_b32_e32 v41, v46, v41, vcc
	v_cndmask_b32_e32 v40, v47, v40, vcc
	v_lshl_add_u64 v[88:89], v[40:41], 0, v[0:1]
	global_load_dwordx4 v[40:43], v[88:89], off
	v_or_b32_e32 v44, 28, v44
	v_ashrrev_i32_e32 v45, 31, v44
	v_cmp_gt_i32_e32 vcc, s96, v44
	v_lshlrev_b64 v[44:45], 11, v[44:45]
	v_lshl_add_u64 v[44:45], s[88:89], 0, v[44:45]
	v_lshl_add_u64 v[44:45], v[44:45], 0, s[80:81]
	v_cndmask_b32_e32 v45, v46, v45, vcc
	v_cndmask_b32_e32 v44, v47, v44, vcc
	v_lshl_add_u64 v[90:91], v[44:45], 0, v[0:1]
	global_load_dwordx4 v[44:47], v[90:91], off
	global_load_dwordx4 v[150:153], v[76:77], off offset:1024
	global_load_dwordx4 v[154:157], v[78:79], off offset:1024
	global_load_dwordx4 v[158:161], v[80:81], off offset:1024
	global_load_dwordx4 v[162:165], v[82:83], off offset:1024
	global_load_dwordx4 v[166:169], v[84:85], off offset:1024
	global_load_dwordx4 v[170:173], v[86:87], off offset:1024
	global_load_dwordx4 v[174:177], v[88:89], off offset:1024
	global_load_dwordx4 v[178:181], v[90:91], off offset:1024
	v_cndmask_b32_e64 v109, 0, 1, s[14:15]
	v_cmp_ne_u32_e32 vcc, 1, v109
	s_waitcnt vmcnt(15)
	v_mov_b32_e32 v92, v13
	v_mov_b32_e32 v13, v15
	v_mov_b32_e32 v93, v14
	v_pk_mul_f32 v[14:15], v[2:3], v[12:13]
	v_pk_mul_f32 v[118:119], v[6:7], v[12:13]
	v_pk_fma_f32 v[14:15], v[8:9], v[92:93], v[14:15]
	v_pk_fma_f32 v[118:119], v[54:55], v[92:93], v[118:119]
	v_add_f32_e32 v14, v14, v15
	s_waitcnt vmcnt(14)
	v_mov_b32_e32 v15, v22
	v_add_f32_dpp v14, v14, v14 quad_perm:[1,0,3,2] row_mask:0xf bank_mask:0xf bound_ctrl:1
	s_nop 1
	v_add_f32_dpp v14, v14, v14 quad_perm:[2,3,0,1] row_mask:0xf bank_mask:0xf bound_ctrl:1
	s_nop 1
	v_add_f32_dpp v14, v14, v14 row_half_mirror row_mask:0xf bank_mask:0xf bound_ctrl:1
	s_nop 1
	v_add_f32_dpp v110, v14, v14 row_mirror row_mask:0xf bank_mask:0xf bound_ctrl:1
	v_mov_b32_e32 v14, v21
	v_mov_b32_e32 v21, v23
	v_pk_mul_f32 v[22:23], v[2:3], v[20:21]
	v_pk_mul_f32 v[128:129], v[10:11], v[20:21]
	v_pk_fma_f32 v[22:23], v[8:9], v[14:15], v[22:23]
	v_pk_fma_f32 v[128:129], v[52:53], v[14:15], v[128:129]
	v_add_f32_e32 v22, v22, v23
	s_waitcnt vmcnt(13)
	v_mov_b32_e32 v23, v26
	v_add_f32_dpp v22, v22, v22 quad_perm:[1,0,3,2] row_mask:0xf bank_mask:0xf bound_ctrl:1
	s_nop 1
	v_add_f32_dpp v22, v22, v22 quad_perm:[2,3,0,1] row_mask:0xf bank_mask:0xf bound_ctrl:1
	s_nop 1
	v_add_f32_dpp v22, v22, v22 row_half_mirror row_mask:0xf bank_mask:0xf bound_ctrl:1
	s_nop 1
	v_add_f32_dpp v111, v22, v22 row_mirror row_mask:0xf bank_mask:0xf bound_ctrl:1
	v_mov_b32_e32 v22, v25
	v_mov_b32_e32 v25, v27
	v_pk_mul_f32 v[26:27], v[2:3], v[24:25]
	v_pk_mul_f32 v[120:121], v[6:7], v[24:25]
	v_pk_fma_f32 v[26:27], v[8:9], v[22:23], v[26:27]
	v_pk_fma_f32 v[120:121], v[54:55], v[22:23], v[120:121]
	v_add_f32_e32 v26, v26, v27
	s_waitcnt vmcnt(12)
; __device__ __forceinline__ float max3f(float a, float b, float c) { float r; asm("v_max3_f32 %0, %1, %2, %3" : "=v"(r) : "v"(a), "v"(b), "v"(c)); return r; }
; __device__ __forceinline__ float dot4(f32x4 a, f32x4 b) { return (a[0] * b[0] + a[1] * b[1]) + (a[2] * b[2] + a[3] * b[3]); }
; __device__ __forceinline__ float grp16_sum(float v) { return sum16(v); }
; __device__ __forceinline__ void smp_batch(const f32x4 (&kx)[8], const f32x4 (&vx)[8], const f32x4 (&qv)[4], float (&m)[4], float (&l)[4], f32x4 (&o)[4]) {
;     ...
;     for (int h = 0; h < 4; ++h) { float s[8];
; #pragma unroll
;         for (int u = 0; u < 8; ++u) s[u] = grp16_sum(dot4(kx[u], qv[h]));
;         const float bm = fmaxf(max3f(max3f(s[0], s[1], s[2]), max3f(s[3], s[4], s[5]), s[6]), s[7]);
;         const bool mv = bm > m[h] + 8.0f;
;         if (__any(mv)) { const float mn = mv ? bm : m[h]; const float al = __builtin_amdgcn_exp2f(m[h] - mn); l[h] *= al; o[h] = o[h] * al; m[h] = mn; }
	v_mov_b32_e32 v27, v30
	v_add_f32_dpp v26, v26, v26 quad_perm:[1,0,3,2] row_mask:0xf bank_mask:0xf bound_ctrl:1
	s_nop 1
	v_add_f32_dpp v26, v26, v26 quad_perm:[2,3,0,1] row_mask:0xf bank_mask:0xf bound_ctrl:1
	s_nop 1
	v_add_f32_dpp v26, v26, v26 row_half_mirror row_mask:0xf bank_mask:0xf bound_ctrl:1
	s_nop 1
	v_add_f32_dpp v112, v26, v26 row_mirror row_mask:0xf bank_mask:0xf bound_ctrl:1
	v_mov_b32_e32 v26, v29
	v_mov_b32_e32 v29, v31
	v_pk_mul_f32 v[30:31], v[2:3], v[28:29]
	v_pk_mul_f32 v[122:123], v[6:7], v[28:29]
	v_pk_fma_f32 v[30:31], v[8:9], v[26:27], v[30:31]
	v_pk_fma_f32 v[122:123], v[54:55], v[26:27], v[122:123]
	v_add_f32_e32 v30, v30, v31
	s_waitcnt vmcnt(11)
	v_mov_b32_e32 v31, v34
	v_pk_mul_f32 v[130:131], v[10:11], v[28:29]
	v_add_f32_dpp v30, v30, v30 quad_perm:[1,0,3,2] row_mask:0xf bank_mask:0xf bound_ctrl:1
	v_pk_fma_f32 v[130:131], v[52:53], v[26:27], v[130:131]
	s_nop 0
	v_add_f32_dpp v30, v30, v30 quad_perm:[2,3,0,1] row_mask:0xf bank_mask:0xf bound_ctrl:1
	s_nop 1
	v_add_f32_dpp v30, v30, v30 row_half_mirror row_mask:0xf bank_mask:0xf bound_ctrl:1
	s_nop 1
	v_add_f32_dpp v113, v30, v30 row_mirror row_mask:0xf bank_mask:0xf bound_ctrl:1
	v_mov_b32_e32 v30, v33
	v_mov_b32_e32 v33, v35
	v_pk_mul_f32 v[34:35], v[2:3], v[32:33]
	s_nop 0
	v_pk_fma_f32 v[34:35], v[8:9], v[30:31], v[34:35]
	s_nop 0
	v_add_f32_e32 v34, v34, v35
	s_waitcnt vmcnt(10)
	v_mov_b32_e32 v35, v38
	v_add_f32_dpp v34, v34, v34 quad_perm:[1,0,3,2] row_mask:0xf bank_mask:0xf bound_ctrl:1
	s_nop 1
	v_add_f32_dpp v34, v34, v34 quad_perm:[2,3,0,1] row_mask:0xf bank_mask:0xf bound_ctrl:1
	s_nop 1
	v_add_f32_dpp v34, v34, v34 row_half_mirror row_mask:0xf bank_mask:0xf bound_ctrl:1
	s_nop 1
	v_add_f32_dpp v114, v34, v34 row_mirror row_mask:0xf bank_mask:0xf bound_ctrl:1
	v_mov_b32_e32 v34, v37
	v_mov_b32_e32 v37, v39
	v_pk_mul_f32 v[38:39], v[2:3], v[36:37]
	v_pk_mul_f32 v[124:125], v[6:7], v[36:37]
	v_pk_fma_f32 v[38:39], v[8:9], v[34:35], v[38:39]
	v_pk_fma_f32 v[124:125], v[54:55], v[34:35], v[124:125]
	v_add_f32_e32 v38, v38, v39
	s_waitcnt vmcnt(9)
	v_mov_b32_e32 v39, v42
	v_pk_mul_f32 v[132:133], v[10:11], v[36:37]
	v_add_f32_dpp v38, v38, v38 quad_perm:[1,0,3,2] row_mask:0xf bank_mask:0xf bound_ctrl:1
	v_pk_fma_f32 v[132:133], v[52:53], v[34:35], v[132:133]
	s_nop 0
	v_add_f32_dpp v38, v38, v38 quad_perm:[2,3,0,1] row_mask:0xf bank_mask:0xf bound_ctrl:1
	s_nop 1
	v_add_f32_dpp v38, v38, v38 row_half_mirror row_mask:0xf bank_mask:0xf bound_ctrl:1
	s_nop 1
	v_add_f32_dpp v115, v38, v38 row_mirror row_mask:0xf bank_mask:0xf bound_ctrl:1
	v_mov_b32_e32 v38, v41
	v_mov_b32_e32 v41, v43
	v_pk_mul_f32 v[42:43], v[2:3], v[40:41]
	v_max3_f32 v117, v113, v114, v115
	s_nop 0
	v_pk_fma_f32 v[42:43], v[8:9], v[38:39], v[42:43]
	s_nop 0
	v_add_f32_e32 v42, v42, v43
	s_waitcnt vmcnt(8)
	v_mov_b32_e32 v43, v46
	v_add_f32_dpp v42, v42, v42 quad_perm:[1,0,3,2] row_mask:0xf bank_mask:0xf bound_ctrl:1
	s_nop 1
	v_add_f32_dpp v42, v42, v42 quad_perm:[2,3,0,1] row_mask:0xf bank_mask:0xf bound_ctrl:1
	s_nop 1
	v_add_f32_dpp v42, v42, v42 row_half_mirror row_mask:0xf bank_mask:0xf bound_ctrl:1
	s_nop 1
	v_add_f32_dpp v116, v42, v42 row_mirror row_mask:0xf bank_mask:0xf bound_ctrl:1
	v_mov_b32_e32 v42, v45
	v_mov_b32_e32 v45, v47
	v_pk_mul_f32 v[46:47], v[2:3], v[44:45]
	v_pk_mul_f32 v[126:127], v[6:7], v[44:45]
	v_pk_fma_f32 v[46:47], v[8:9], v[42:43], v[46:47]
	v_pk_fma_f32 v[126:127], v[54:55], v[42:43], v[126:127]
	v_add_f32_e32 v46, v46, v47
	v_max3_f32 v47, v110, v111, v112
	v_pk_mul_f32 v[134:135], v[10:11], v[44:45]
	v_max3_f32 v47, v47, v117, v116
	v_add_f32_e32 v117, 0x41000000, v97
	v_add_f32_dpp v46, v46, v46 quad_perm:[1,0,3,2] row_mask:0xf bank_mask:0xf bound_ctrl:1
	v_max_f32_e32 v47, v47, v47
	v_pk_fma_f32 v[134:135], v[52:53], v[42:43], v[134:135]
	v_add_f32_dpp v46, v46, v46 quad_perm:[2,3,0,1] row_mask:0xf bank_mask:0xf bound_ctrl:1
	s_nop 1
	v_add_f32_dpp v46, v46, v46 row_half_mirror row_mask:0xf bank_mask:0xf bound_ctrl:1
	s_nop 1
	v_add_f32_dpp v46, v46, v46 row_mirror row_mask:0xf bank_mask:0xf bound_ctrl:1
	v_max_f32_e32 v47, v47, v46
	v_cmp_gt_f32_e64 s[14:15], v47, v117
	v_add_f32_e32 v117, v118, v119
	v_pk_mul_f32 v[118:119], v[6:7], v[20:21]
	s_nop 0
	v_pk_fma_f32 v[118:119], v[54:55], v[14:15], v[118:119]
	v_add_f32_dpp v117, v117, v117 quad_perm:[1,0,3,2] row_mask:0xf bank_mask:0xf bound_ctrl:1
	v_add_f32_e32 v118, v118, v119
	s_nop 0
	v_add_f32_dpp v117, v117, v117 quad_perm:[2,3,0,1] row_mask:0xf bank_mask:0xf bound_ctrl:1
	v_add_f32_dpp v118, v118, v118 quad_perm:[1,0,3,2] row_mask:0xf bank_mask:0xf bound_ctrl:1
	s_nop 0
	v_add_f32_dpp v117, v117, v117 row_half_mirror row_mask:0xf bank_mask:0xf bound_ctrl:1
	v_add_f32_dpp v118, v118, v118 quad_perm:[2,3,0,1] row_mask:0xf bank_mask:0xf bound_ctrl:1
	s_nop 0
	v_add_f32_dpp v117, v117, v117 row_mirror row_mask:0xf bank_mask:0xf bound_ctrl:1
	v_add_f32_dpp v118, v118, v118 row_half_mirror row_mask:0xf bank_mask:0xf bound_ctrl:1
	s_nop 1
	v_add_f32_dpp v119, v118, v118 row_mirror row_mask:0xf bank_mask:0xf bound_ctrl:1
	v_add_f32_e32 v118, v120, v121
	s_nop 1
	v_add_f32_dpp v118, v118, v118 quad_perm:[1,0,3,2] row_mask:0xf bank_mask:0xf bound_ctrl:1
	s_nop 1
	v_add_f32_dpp v118, v118, v118 quad_perm:[2,3,0,1] row_mask:0xf bank_mask:0xf bound_ctrl:1
	s_nop 1
	v_add_f32_dpp v118, v118, v118 row_half_mirror row_mask:0xf bank_mask:0xf bound_ctrl:1
	s_nop 1
	v_add_f32_dpp v120, v118, v118 row_mirror row_mask:0xf bank_mask:0xf bound_ctrl:1
	v_add_f32_e32 v118, v122, v123
	v_pk_mul_f32 v[122:123], v[6:7], v[32:33]
	s_nop 0
	v_add_f32_dpp v118, v118, v118 quad_perm:[1,0,3,2] row_mask:0xf bank_mask:0xf bound_ctrl:1
; __device__ __forceinline__ float max3f(float a, float b, float c) { float r; asm("v_max3_f32 %0, %1, %2, %3" : "=v"(r) : "v"(a), "v"(b), "v"(c)); return r; }
; __device__ __forceinline__ float dot4(f32x4 a, f32x4 b) { return (a[0] * b[0] + a[1] * b[1]) + (a[2] * b[2] + a[3] * b[3]); }
; __device__ __forceinline__ float grp16_sum(float v) { return sum16(v); }
; __device__ __forceinline__ void smp_batch(const f32x4 (&kx)[8], const f32x4 (&vx)[8], const f32x4 (&qv)[4], float (&m)[4], float (&l)[4], f32x4 (&o)[4]) {
;     ...
;     for (int h = 0; h < 4; ++h) { float s[8];
; #pragma unroll
;         for (int u = 0; u < 8; ++u) s[u] = grp16_sum(dot4(kx[u], qv[h]));
;         const float bm = fmaxf(max3f(max3f(s[0], s[1], s[2]), max3f(s[3], s[4], s[5]), s[6]), s[7]);
;         const bool mv = bm > m[h] + 8.0f;
;         if (__any(mv)) { const float mn = mv ? bm : m[h]; const float al = __builtin_amdgcn_exp2f(m[h] - mn); l[h] *= al; o[h] = o[h] * al; m[h] = mn; }
	v_pk_fma_f32 v[122:123], v[54:55], v[30:31], v[122:123]
	s_nop 0
	v_add_f32_dpp v118, v118, v118 quad_perm:[2,3,0,1] row_mask:0xf bank_mask:0xf bound_ctrl:1
	s_nop 1
	v_add_f32_dpp v118, v118, v118 row_half_mirror row_mask:0xf bank_mask:0xf bound_ctrl:1
	s_nop 1
	v_add_f32_dpp v121, v118, v118 row_mirror row_mask:0xf bank_mask:0xf bound_ctrl:1
	v_add_f32_e32 v118, v122, v123
	s_nop 1
	v_add_f32_dpp v118, v118, v118 quad_perm:[1,0,3,2] row_mask:0xf bank_mask:0xf bound_ctrl:1
	s_nop 1
	v_add_f32_dpp v118, v118, v118 quad_perm:[2,3,0,1] row_mask:0xf bank_mask:0xf bound_ctrl:1
	s_nop 1
	v_add_f32_dpp v118, v118, v118 row_half_mirror row_mask:0xf bank_mask:0xf bound_ctrl:1
	s_nop 1
	v_add_f32_dpp v122, v118, v118 row_mirror row_mask:0xf bank_mask:0xf bound_ctrl:1
	v_add_f32_e32 v118, v124, v125
	v_pk_mul_f32 v[124:125], v[6:7], v[40:41]
	s_nop 0
	v_add_f32_dpp v118, v118, v118 quad_perm:[1,0,3,2] row_mask:0xf bank_mask:0xf bound_ctrl:1
	v_pk_fma_f32 v[124:125], v[54:55], v[38:39], v[124:125]
	s_nop 0
	v_add_f32_dpp v118, v118, v118 quad_perm:[2,3,0,1] row_mask:0xf bank_mask:0xf bound_ctrl:1
	s_nop 1
	v_add_f32_dpp v118, v118, v118 row_half_mirror row_mask:0xf bank_mask:0xf bound_ctrl:1
	s_nop 1
	v_add_f32_dpp v123, v118, v118 row_mirror row_mask:0xf bank_mask:0xf bound_ctrl:1
	v_add_f32_e32 v118, v124, v125
	v_max3_f32 v125, v117, v119, v120
	s_nop 1
	v_add_f32_dpp v118, v118, v118 quad_perm:[1,0,3,2] row_mask:0xf bank_mask:0xf bound_ctrl:1
	s_nop 1
	v_add_f32_dpp v118, v118, v118 quad_perm:[2,3,0,1] row_mask:0xf bank_mask:0xf bound_ctrl:1
	s_nop 1
	v_add_f32_dpp v118, v118, v118 row_half_mirror row_mask:0xf bank_mask:0xf bound_ctrl:1
	s_nop 1
	v_add_f32_dpp v124, v118, v118 row_mirror row_mask:0xf bank_mask:0xf bound_ctrl:1
	v_add_f32_e32 v118, v126, v127
	v_max3_f32 v126, v121, v122, v123
	s_nop 0
	v_max3_f32 v125, v125, v126, v124
	v_add_f32_e32 v126, 0x41000000, v95
	v_add_f32_dpp v118, v118, v118 quad_perm:[1,0,3,2] row_mask:0xf bank_mask:0xf bound_ctrl:1
	v_max_f32_e32 v125, v125, v125
	s_nop 0
	v_add_f32_dpp v118, v118, v118 quad_perm:[2,3,0,1] row_mask:0xf bank_mask:0xf bound_ctrl:1
	s_nop 1
	v_add_f32_dpp v118, v118, v118 row_half_mirror row_mask:0xf bank_mask:0xf bound_ctrl:1
	s_nop 1
	v_add_f32_dpp v118, v118, v118 row_mirror row_mask:0xf bank_mask:0xf bound_ctrl:1
	v_max_f32_e32 v125, v125, v118
	v_cmp_gt_f32_e64 s[20:21], v125, v126
	v_pk_mul_f32 v[126:127], v[10:11], v[12:13]
	v_pk_mul_f32 v[12:13], v[18:19], v[12:13]
	v_pk_fma_f32 v[126:127], v[52:53], v[92:93], v[126:127]
	v_pk_fma_f32 v[12:13], v[50:51], v[92:93], v[12:13]
	v_add_f32_e32 v126, v126, v127
	v_add_f32_e32 v127, v128, v129
	v_pk_mul_f32 v[128:129], v[10:11], v[24:25]
	v_add_f32_dpp v126, v126, v126 quad_perm:[1,0,3,2] row_mask:0xf bank_mask:0xf bound_ctrl:1
	v_pk_fma_f32 v[128:129], v[52:53], v[22:23], v[128:129]
	v_add_f32_dpp v127, v127, v127 quad_perm:[1,0,3,2] row_mask:0xf bank_mask:0xf bound_ctrl:1
	v_add_f32_e32 v128, v128, v129
	v_add_f32_e32 v129, v130, v131
	v_pk_mul_f32 v[130:131], v[10:11], v[32:33]
	v_add_f32_dpp v128, v128, v128 quad_perm:[1,0,3,2] row_mask:0xf bank_mask:0xf bound_ctrl:1
	v_pk_fma_f32 v[130:131], v[52:53], v[30:31], v[130:131]
	v_add_f32_dpp v126, v126, v126 quad_perm:[2,3,0,1] row_mask:0xf bank_mask:0xf bound_ctrl:1
	v_add_f32_e32 v130, v130, v131
	v_add_f32_e32 v131, v132, v133
	v_pk_mul_f32 v[132:133], v[10:11], v[40:41]
	v_add_f32_dpp v127, v127, v127 quad_perm:[2,3,0,1] row_mask:0xf bank_mask:0xf bound_ctrl:1
	v_pk_fma_f32 v[132:133], v[52:53], v[38:39], v[132:133]
	v_add_f32_dpp v128, v128, v128 quad_perm:[2,3,0,1] row_mask:0xf bank_mask:0xf bound_ctrl:1
	v_add_f32_e32 v132, v132, v133
	v_add_f32_dpp v129, v129, v129 quad_perm:[1,0,3,2] row_mask:0xf bank_mask:0xf bound_ctrl:1
	v_add_f32_dpp v130, v130, v130 quad_perm:[1,0,3,2] row_mask:0xf bank_mask:0xf bound_ctrl:1
	v_add_f32_dpp v131, v131, v131 quad_perm:[1,0,3,2] row_mask:0xf bank_mask:0xf bound_ctrl:1
	v_add_f32_dpp v132, v132, v132 quad_perm:[1,0,3,2] row_mask:0xf bank_mask:0xf bound_ctrl:1
	v_add_f32_e32 v133, v134, v135
	v_add_f32_dpp v126, v126, v126 row_half_mirror row_mask:0xf bank_mask:0xf bound_ctrl:1
	v_add_f32_dpp v127, v127, v127 row_half_mirror row_mask:0xf bank_mask:0xf bound_ctrl:1
	v_add_f32_dpp v128, v128, v128 row_half_mirror row_mask:0xf bank_mask:0xf bound_ctrl:1
	v_add_f32_dpp v129, v129, v129 quad_perm:[2,3,0,1] row_mask:0xf bank_mask:0xf bound_ctrl:1
	v_add_f32_dpp v130, v130, v130 quad_perm:[2,3,0,1] row_mask:0xf bank_mask:0xf bound_ctrl:1
	v_add_f32_dpp v131, v131, v131 quad_perm:[2,3,0,1] row_mask:0xf bank_mask:0xf bound_ctrl:1
	v_add_f32_dpp v132, v132, v132 quad_perm:[2,3,0,1] row_mask:0xf bank_mask:0xf bound_ctrl:1
	v_add_f32_dpp v133, v133, v133 quad_perm:[1,0,3,2] row_mask:0xf bank_mask:0xf bound_ctrl:1
	v_add_f32_dpp v126, v126, v126 row_mirror row_mask:0xf bank_mask:0xf bound_ctrl:1
	v_add_f32_dpp v127, v127, v127 row_mirror row_mask:0xf bank_mask:0xf bound_ctrl:1
	v_add_f32_dpp v128, v128, v128 row_mirror row_mask:0xf bank_mask:0xf bound_ctrl:1
	v_add_f32_dpp v129, v129, v129 row_half_mirror row_mask:0xf bank_mask:0xf bound_ctrl:1
	v_add_f32_dpp v130, v130, v130 row_half_mirror row_mask:0xf bank_mask:0xf bound_ctrl:1
	v_add_f32_dpp v131, v131, v131 row_half_mirror row_mask:0xf bank_mask:0xf bound_ctrl:1
	v_add_f32_dpp v132, v132, v132 row_half_mirror row_mask:0xf bank_mask:0xf bound_ctrl:1
	v_add_f32_dpp v133, v133, v133 quad_perm:[2,3,0,1] row_mask:0xf bank_mask:0xf bound_ctrl:1
	v_max3_f32 v134, v126, v127, v128
	v_add_f32_e32 v12, v12, v13
	v_add_f32_dpp v129, v129, v129 row_mirror row_mask:0xf bank_mask:0xf bound_ctrl:1
; __device__ __forceinline__ float max3f(float a, float b, float c) { float r; asm("v_max3_f32 %0, %1, %2, %3" : "=v"(r) : "v"(a), "v"(b), "v"(c)); return r; }
; __device__ __forceinline__ float dot4(f32x4 a, f32x4 b) { return (a[0] * b[0] + a[1] * b[1]) + (a[2] * b[2] + a[3] * b[3]); }
; __device__ __forceinline__ float grp16_sum(float v) { return sum16(v); }
; __device__ __forceinline__ void smp_batch(const f32x4 (&kx)[8], const f32x4 (&vx)[8], const f32x4 (&qv)[4], float (&m)[4], float (&l)[4], f32x4 (&o)[4]) {
;     ...
;     for (int h = 0; h < 4; ++h) { float s[8];
; #pragma unroll
;         for (int u = 0; u < 8; ++u) s[u] = grp16_sum(dot4(kx[u], qv[h]));
;         const float bm = fmaxf(max3f(max3f(s[0], s[1], s[2]), max3f(s[3], s[4], s[5]), s[6]), s[7]);
;         const bool mv = bm > m[h] + 8.0f;
;         if (__any(mv)) { const float mn = mv ? bm : m[h]; const float al = __builtin_amdgcn_exp2f(m[h] - mn); l[h] *= al; o[h] = o[h] * al; m[h] = mn; }
; #pragma unroll
;         for (int u = 0; u < 8; ++u) { const float p = __builtin_amdgcn_exp2f(s[u] - m[h]); l[h] += p; o[h] = o[h] + vx[u] * p; } }
	v_add_f32_dpp v130, v130, v130 row_mirror row_mask:0xf bank_mask:0xf bound_ctrl:1
	v_add_f32_dpp v131, v131, v131 row_mirror row_mask:0xf bank_mask:0xf bound_ctrl:1
	v_add_f32_dpp v132, v132, v132 row_mirror row_mask:0xf bank_mask:0xf bound_ctrl:1
	v_add_f32_dpp v133, v133, v133 row_half_mirror row_mask:0xf bank_mask:0xf bound_ctrl:1
	v_max3_f32 v135, v129, v130, v131
	v_add_f32_dpp v12, v12, v12 quad_perm:[1,0,3,2] row_mask:0xf bank_mask:0xf bound_ctrl:1
	v_max3_f32 v134, v134, v135, v132
	v_add_f32_e32 v135, 0x41000000, v94
	v_add_f32_dpp v133, v133, v133 row_mirror row_mask:0xf bank_mask:0xf bound_ctrl:1
	v_max_f32_e32 v134, v134, v134
	v_add_f32_dpp v12, v12, v12 quad_perm:[2,3,0,1] row_mask:0xf bank_mask:0xf bound_ctrl:1
	v_max_f32_e32 v134, v134, v133
	v_cmp_gt_f32_e64 s[22:23], v134, v135
	v_add_f32_dpp v12, v12, v12 row_half_mirror row_mask:0xf bank_mask:0xf bound_ctrl:1
	s_cmp_eq_u64 s[20:21], 0
	s_cselect_b64 s[16:17], -1, 0
	v_add_f32_dpp v135, v12, v12 row_mirror row_mask:0xf bank_mask:0xf bound_ctrl:1
	v_pk_mul_f32 v[12:13], v[18:19], v[20:21]
	s_cmp_eq_u64 s[14:15], 0
	v_pk_fma_f32 v[12:13], v[50:51], v[14:15], v[12:13]
	s_cselect_b64 s[18:19], -1, 0
	v_add_f32_e32 v12, v12, v13
	s_nop 1
	v_add_f32_dpp v12, v12, v12 quad_perm:[1,0,3,2] row_mask:0xf bank_mask:0xf bound_ctrl:1
	s_nop 1
	v_add_f32_dpp v12, v12, v12 quad_perm:[2,3,0,1] row_mask:0xf bank_mask:0xf bound_ctrl:1
	s_nop 1
	v_add_f32_dpp v12, v12, v12 row_half_mirror row_mask:0xf bank_mask:0xf bound_ctrl:1
	s_nop 1
	v_add_f32_dpp v136, v12, v12 row_mirror row_mask:0xf bank_mask:0xf bound_ctrl:1
	v_pk_mul_f32 v[12:13], v[18:19], v[24:25]
	s_nop 0
	v_pk_fma_f32 v[12:13], v[50:51], v[22:23], v[12:13]
	s_nop 0
	v_add_f32_e32 v12, v12, v13
	s_nop 1
	v_add_f32_dpp v12, v12, v12 quad_perm:[1,0,3,2] row_mask:0xf bank_mask:0xf bound_ctrl:1
	s_nop 1
	v_add_f32_dpp v12, v12, v12 quad_perm:[2,3,0,1] row_mask:0xf bank_mask:0xf bound_ctrl:1
	s_nop 1
	v_add_f32_dpp v12, v12, v12 row_half_mirror row_mask:0xf bank_mask:0xf bound_ctrl:1
	s_nop 1
	v_add_f32_dpp v137, v12, v12 row_mirror row_mask:0xf bank_mask:0xf bound_ctrl:1
	v_pk_mul_f32 v[12:13], v[18:19], v[28:29]
	s_nop 0
	v_pk_fma_f32 v[12:13], v[50:51], v[26:27], v[12:13]
	s_nop 0
	v_add_f32_e32 v12, v12, v13
	s_nop 1
	v_add_f32_dpp v12, v12, v12 quad_perm:[1,0,3,2] row_mask:0xf bank_mask:0xf bound_ctrl:1
	s_nop 1
	v_add_f32_dpp v12, v12, v12 quad_perm:[2,3,0,1] row_mask:0xf bank_mask:0xf bound_ctrl:1
	s_nop 1
	v_add_f32_dpp v12, v12, v12 row_half_mirror row_mask:0xf bank_mask:0xf bound_ctrl:1
	s_nop 1
	v_add_f32_dpp v138, v12, v12 row_mirror row_mask:0xf bank_mask:0xf bound_ctrl:1
	v_pk_mul_f32 v[12:13], v[18:19], v[32:33]
	s_nop 0
	v_pk_fma_f32 v[12:13], v[50:51], v[30:31], v[12:13]
	s_nop 0
	v_add_f32_e32 v12, v12, v13
	s_nop 1
	v_add_f32_dpp v12, v12, v12 quad_perm:[1,0,3,2] row_mask:0xf bank_mask:0xf bound_ctrl:1
	s_nop 1
	v_add_f32_dpp v12, v12, v12 quad_perm:[2,3,0,1] row_mask:0xf bank_mask:0xf bound_ctrl:1
	s_nop 1
	v_add_f32_dpp v12, v12, v12 row_half_mirror row_mask:0xf bank_mask:0xf bound_ctrl:1
	s_nop 1
	v_add_f32_dpp v139, v12, v12 row_mirror row_mask:0xf bank_mask:0xf bound_ctrl:1
	v_pk_mul_f32 v[12:13], v[18:19], v[36:37]
	s_nop 0
	v_pk_fma_f32 v[12:13], v[50:51], v[34:35], v[12:13]
	s_nop 0
	v_add_f32_e32 v12, v12, v13
	s_nop 1
	v_add_f32_dpp v12, v12, v12 quad_perm:[1,0,3,2] row_mask:0xf bank_mask:0xf bound_ctrl:1
	s_nop 1
	v_add_f32_dpp v12, v12, v12 quad_perm:[2,3,0,1] row_mask:0xf bank_mask:0xf bound_ctrl:1
	s_nop 1
	v_add_f32_dpp v12, v12, v12 row_half_mirror row_mask:0xf bank_mask:0xf bound_ctrl:1
	s_nop 1
	v_add_f32_dpp v140, v12, v12 row_mirror row_mask:0xf bank_mask:0xf bound_ctrl:1
	v_pk_mul_f32 v[12:13], v[18:19], v[40:41]
	s_nop 0
	v_pk_fma_f32 v[12:13], v[50:51], v[38:39], v[12:13]
	s_nop 0
	v_add_f32_e32 v12, v12, v13
	s_nop 1
	v_add_f32_dpp v12, v12, v12 quad_perm:[1,0,3,2] row_mask:0xf bank_mask:0xf bound_ctrl:1
	s_nop 1
	v_add_f32_dpp v12, v12, v12 quad_perm:[2,3,0,1] row_mask:0xf bank_mask:0xf bound_ctrl:1
	s_nop 1
	v_add_f32_dpp v12, v12, v12 row_half_mirror row_mask:0xf bank_mask:0xf bound_ctrl:1
	s_nop 1
	v_add_f32_dpp v141, v12, v12 row_mirror row_mask:0xf bank_mask:0xf bound_ctrl:1
	v_pk_mul_f32 v[12:13], v[18:19], v[44:45]
	v_cndmask_b32_e64 v45, v97, v47, s[14:15]
	v_pk_fma_f32 v[12:13], v[50:51], v[42:43], v[12:13]
	v_sub_f32_e32 v44, v97, v45
	v_add_f32_e32 v12, v12, v13
	v_max3_f32 v13, v138, v139, v140
	v_exp_f32_e32 v44, v44
	v_cndmask_b32_e64 v97, v45, v97, s[18:19]
	v_add_f32_dpp v12, v12, v12 quad_perm:[1,0,3,2] row_mask:0xf bank_mask:0xf bound_ctrl:1
	v_cndmask_b32_e64 v47, v95, v125, s[20:21]
	s_mov_b64 s[14:15], 0
	v_add_f32_dpp v12, v12, v12 quad_perm:[2,3,0,1] row_mask:0xf bank_mask:0xf bound_ctrl:1
	s_nop 1
	v_add_f32_dpp v12, v12, v12 row_half_mirror row_mask:0xf bank_mask:0xf bound_ctrl:1
	s_nop 1
	v_add_f32_dpp v142, v12, v12 row_mirror row_mask:0xf bank_mask:0xf bound_ctrl:1
	v_max3_f32 v12, v135, v136, v137
	s_nop 0
	v_max3_f32 v12, v12, v13, v141
	s_nop 0
	v_max_f32_e32 v12, v12, v12
	v_max_f32_e32 v143, v12, v142
	v_add_f32_e32 v12, 0x41000000, v5
	v_cmp_gt_f32_e64 s[28:29], v143, v12
	v_pk_mul_f32 v[80:81], v[72:73], v[44:45] op_sel_hi:[1,0]
	v_pk_mul_f32 v[82:83], v[74:75], v[44:45] op_sel_hi:[1,0]
	v_sub_f32_e32 v45, v110, v97
	v_cndmask_b32_e64 v72, v80, v72, s[18:19]
	v_exp_f32_e32 v80, v45
	v_sub_f32_e32 v45, v111, v97
	v_sub_f32_e32 v84, v95, v47
	v_cndmask_b32_e64 v74, v82, v74, s[18:19]
	v_exp_f32_e32 v82, v45
	v_sub_f32_e32 v45, v112, v97
	v_exp_f32_e32 v84, v84
	v_exp_f32_e32 v90, v45
	v_sub_f32_e32 v45, v113, v97
	v_exp_f32_e32 v92, v45
	v_sub_f32_e32 v45, v114, v97
	v_exp_f32_e32 v110, v45
	v_sub_f32_e32 v45, v115, v97
	v_exp_f32_e32 v112, v45
	v_sub_f32_e32 v45, v116, v97
	v_pk_mul_f32 v[86:87], v[66:67], v[84:85] op_sel_hi:[1,0]
	v_pk_mul_f32 v[88:89], v[68:69], v[84:85] op_sel_hi:[1,0]
	v_cndmask_b32_e64 v75, v83, v75, s[18:19]
	v_cndmask_b32_e64 v73, v81, v73, s[18:19]
	v_exp_f32_e32 v114, v45
	v_sub_f32_e32 v45, v46, v97
	v_mov_b32_e32 v85, v44
	v_cndmask_b32_e64 v95, v47, v95, s[16:17]
	v_exp_f32_e32 v46, v45
	v_pk_mul_f32 v[44:45], v[70:71], v[84:85]
	v_sub_f32_e32 v47, v117, v95
	v_cndmask_b32_e64 v44, v44, v70, s[16:17]
	v_exp_f32_e32 v70, v47
	v_sub_f32_e32 v47, v119, v95
	v_cndmask_b32_e64 v45, v45, v71, s[18:19]
	v_mov_b32_e32 v71, v80
	v_pk_add_f32 v[44:45], v[70:71], v[44:45]
	v_mov_b32_e32 v85, v92
	v_cndmask_b32_e64 v69, v89, v69, s[16:17]
	v_cndmask_b32_e64 v68, v88, v68, s[16:17]
	v_cndmask_b32_e64 v67, v87, v67, s[16:17]
	v_cndmask_b32_e64 v66, v86, v66, s[16:17]
	s_cmp_eq_u64 s[28:29], 0
	s_cselect_b64 s[24:25], -1, 0
	s_cmp_eq_u64 s[22:23], 0
	s_cselect_b64 s[26:27], -1, 0
	v_cndmask_b32_e64 v89, v5, v143, s[28:29]
	s_mov_b32 s16, 32
	s_and_b64 vcc, exec, vcc
	s_waitcnt vmcnt(7)
; __device__ __forceinline__ void smp_batch(const f32x4 (&kx)[8], const f32x4 (&vx)[8], const f32x4 (&qv)[4], float (&m)[4], float (&l)[4], f32x4 (&o)[4]) {
;     ...
;         if (__any(mv)) { const float mn = mv ? bm : m[h]; const float al = __builtin_amdgcn_exp2f(m[h] - mn); l[h] *= al; o[h] = o[h] * al; m[h] = mn; }
; #pragma unroll
;         for (int u = 0; u < 8; ++u) { const float p = __builtin_amdgcn_exp2f(s[u] - m[h]); l[h] += p; o[h] = o[h] + vx[u] * p; } }
	v_mov_b64 v[12:13], v[150:151]
	v_mov_b64 v[14:15], v[152:153]
	v_pk_fma_f32 v[72:73], v[12:13], v[80:81], v[72:73] op_sel_hi:[1,0,1]
	v_pk_fma_f32 v[74:75], v[14:15], v[80:81], v[74:75] op_sel_hi:[1,0,1]
	s_waitcnt vmcnt(6)
	v_mov_b64 v[20:21], v[154:155]
	v_mov_b64 v[22:23], v[156:157]
	v_pk_fma_f32 v[72:73], v[20:21], v[82:83], v[72:73] op_sel_hi:[1,0,1]
	v_pk_fma_f32 v[74:75], v[22:23], v[82:83], v[74:75] op_sel_hi:[1,0,1]
	s_waitcnt vmcnt(5)
	v_mov_b64 v[24:25], v[158:159]
	v_mov_b64 v[26:27], v[160:161]
	v_pk_fma_f32 v[72:73], v[24:25], v[90:91], v[72:73] op_sel_hi:[1,0,1]
	v_pk_fma_f32 v[74:75], v[26:27], v[90:91], v[74:75] op_sel_hi:[1,0,1]
	v_exp_f32_e32 v80, v47
	v_sub_f32_e32 v47, v120, v95
	s_waitcnt vmcnt(4)
	v_mov_b64 v[28:29], v[162:163]
	v_mov_b64 v[30:31], v[164:165]
	v_pk_fma_f32 v[74:75], v[30:31], v[92:93], v[74:75] op_sel_hi:[1,0,1]
	v_pk_fma_f32 v[72:73], v[28:29], v[92:93], v[72:73] op_sel_hi:[1,0,1]
	v_mov_b32_e32 v81, v82
	v_exp_f32_e32 v82, v47
	v_sub_f32_e32 v47, v121, v95
	s_waitcnt vmcnt(3)
	v_mov_b64 v[32:33], v[166:167]
	v_mov_b64 v[34:35], v[168:169]
	v_pk_fma_f32 v[72:73], v[32:33], v[110:111], v[72:73] op_sel_hi:[1,0,1]
	v_pk_fma_f32 v[74:75], v[34:35], v[110:111], v[74:75] op_sel_hi:[1,0,1]
	v_exp_f32_e32 v84, v47
	v_sub_f32_e32 v47, v122, v95
	s_waitcnt vmcnt(2)
	v_mov_b64 v[36:37], v[170:171]
	v_mov_b64 v[38:39], v[172:173]
	v_pk_fma_f32 v[74:75], v[38:39], v[112:113], v[74:75] op_sel_hi:[1,0,1]
	v_pk_fma_f32 v[72:73], v[36:37], v[112:113], v[72:73] op_sel_hi:[1,0,1]
	v_mov_b32_e32 v83, v90
	v_exp_f32_e32 v90, v47
	v_sub_f32_e32 v47, v123, v95
	s_waitcnt vmcnt(1)
	v_mov_b64 v[40:41], v[174:175]
	v_mov_b64 v[42:43], v[176:177]
	v_pk_fma_f32 v[72:73], v[40:41], v[114:115], v[72:73] op_sel_hi:[1,0,1]
	v_pk_fma_f32 v[74:75], v[42:43], v[114:115], v[74:75] op_sel_hi:[1,0,1]
	v_pk_add_f32 v[44:45], v[80:81], v[44:45]
	v_exp_f32_e32 v92, v47
	v_sub_f32_e32 v47, v124, v95
	v_pk_add_f32 v[44:45], v[82:83], v[44:45]
	v_mov_b32_e32 v91, v110
	v_exp_f32_e32 v110, v47
	s_waitcnt vmcnt(0)
	v_mov_b64 v[76:77], v[178:179]
	v_mov_b64 v[78:79], v[180:181]
	v_pk_fma_f32 v[74:75], v[78:79], v[46:47], v[74:75] op_sel_hi:[1,0,1]
	v_pk_fma_f32 v[72:73], v[76:77], v[46:47], v[72:73] op_sel_hi:[1,0,1]
	v_pk_fma_f32 v[66:67], v[12:13], v[70:71], v[66:67] op_sel_hi:[1,0,1]
	v_pk_fma_f32 v[68:69], v[14:15], v[70:71], v[68:69] op_sel_hi:[1,0,1]
	v_sub_f32_e32 v47, v118, v95
	v_pk_add_f32 v[44:45], v[84:85], v[44:45]
	v_pk_fma_f32 v[68:69], v[22:23], v[80:81], v[68:69] op_sel_hi:[1,0,1]
	v_pk_fma_f32 v[66:67], v[20:21], v[80:81], v[66:67] op_sel_hi:[1,0,1]
	v_exp_f32_e32 v80, v47
	v_pk_add_f32 v[44:45], v[90:91], v[44:45]
	v_mov_b32_e32 v93, v112
	v_pk_add_f32 v[44:45], v[92:93], v[44:45]
	v_mov_b32_e32 v111, v114
	v_pk_add_f32 v[44:45], v[110:111], v[44:45]
	v_mov_b32_e32 v81, v46
	v_pk_add_f32 v[70:71], v[80:81], v[44:45]
	v_cndmask_b32_e64 v45, v94, v134, s[22:23]
	v_pk_fma_f32 v[66:67], v[24:25], v[82:83], v[66:67] op_sel_hi:[1,0,1]
	v_pk_fma_f32 v[68:69], v[26:27], v[82:83], v[68:69] op_sel_hi:[1,0,1]
	v_sub_f32_e32 v44, v94, v45
	v_pk_fma_f32 v[68:69], v[30:31], v[84:85], v[68:69] op_sel_hi:[1,0,1]
	v_pk_fma_f32 v[66:67], v[28:29], v[84:85], v[66:67] op_sel_hi:[1,0,1]
	v_exp_f32_e32 v44, v44
	v_pk_fma_f32 v[66:67], v[32:33], v[90:91], v[66:67] op_sel_hi:[1,0,1]
	v_pk_fma_f32 v[68:69], v[34:35], v[90:91], v[68:69] op_sel_hi:[1,0,1]
	v_pk_fma_f32 v[66:67], v[36:37], v[92:93], v[66:67] op_sel_hi:[1,0,1]
	v_pk_fma_f32 v[68:69], v[38:39], v[92:93], v[68:69] op_sel_hi:[1,0,1]
	v_pk_fma_f32 v[66:67], v[40:41], v[110:111], v[66:67] op_sel_hi:[1,0,1]
	v_pk_fma_f32 v[68:69], v[42:43], v[110:111], v[68:69] op_sel_hi:[1,0,1]
	v_cndmask_b32_e64 v94, v45, v94, s[26:27]
	v_pk_fma_f32 v[68:69], v[78:79], v[80:81], v[68:69] op_sel_hi:[1,0,1]
	v_pk_fma_f32 v[66:67], v[76:77], v[80:81], v[66:67] op_sel_hi:[1,0,1]
	v_pk_mul_f32 v[46:47], v[62:63], v[44:45] op_sel_hi:[1,0]
	v_pk_mul_f32 v[80:81], v[64:65], v[44:45] op_sel_hi:[1,0]
	v_sub_f32_e32 v45, v126, v94
	v_cndmask_b32_e64 v46, v46, v62, s[26:27]
	v_exp_f32_e32 v62, v45
	v_sub_f32_e32 v45, v127, v94
	v_sub_f32_e32 v82, v5, v89
	v_cndmask_b32_e64 v64, v80, v64, s[26:27]
	v_exp_f32_e32 v80, v45
	v_sub_f32_e32 v45, v128, v94
	v_exp_f32_e32 v82, v82
	v_exp_f32_e32 v88, v45
	v_sub_f32_e32 v45, v129, v94
	v_exp_f32_e32 v90, v45
	v_sub_f32_e32 v45, v130, v94
	v_exp_f32_e32 v92, v45
	v_sub_f32_e32 v45, v131, v94
	v_exp_f32_e32 v110, v45
	v_sub_f32_e32 v45, v132, v94
	v_pk_mul_f32 v[84:85], v[58:59], v[82:83] op_sel_hi:[1,0]
	v_pk_mul_f32 v[86:87], v[56:57], v[82:83] op_sel_hi:[1,0]
	v_exp_f32_e32 v112, v45
	v_sub_f32_e32 v45, v133, v94
	v_mov_b32_e32 v83, v44
	v_exp_f32_e32 v114, v45
	v_pk_mul_f32 v[44:45], v[60:61], v[82:83]
	v_cndmask_b32_e64 v5, v89, v5, s[24:25]
	v_cndmask_b32_e64 v44, v44, v60, s[24:25]
	v_sub_f32_e32 v60, v135, v5
	v_exp_f32_e32 v60, v60
	v_cndmask_b32_e64 v47, v47, v63, s[26:27]
	v_pk_fma_f32 v[46:47], v[12:13], v[62:63], v[46:47] op_sel_hi:[1,0,1]
	v_cndmask_b32_e64 v45, v45, v61, s[26:27]
	v_pk_fma_f32 v[46:47], v[20:21], v[80:81], v[46:47] op_sel_hi:[1,0,1]
	v_mov_b32_e32 v61, v62
	v_cndmask_b32_e64 v65, v81, v65, s[26:27]
	v_pk_fma_f32 v[46:47], v[24:25], v[88:89], v[46:47] op_sel_hi:[1,0,1]
	v_pk_add_f32 v[44:45], v[60:61], v[44:45]
	v_sub_f32_e32 v61, v136, v5
; #define LAS __attribute__((address_space(3)))
; __device__ __forceinline__ float xhalf_other(float v, int hh) { auto rr = __builtin_amdgcn_permlane32_swap(__float_as_uint(v), __float_as_uint(v), false, false); return __uint_as_float(hh ? rr[0] : rr[1]); }
; __device__ __forceinline__ void smp_batch(const f32x4 (&kx)[8], const f32x4 (&vx)[8], const f32x4 (&qv)[4], float (&m)[4], float (&l)[4], f32x4 (&o)[4]) {
;     ...
;         if (__any(mv)) { const float mn = mv ? bm : m[h]; const float al = __builtin_amdgcn_exp2f(m[h] - mn); l[h] *= al; o[h] = o[h] * al; m[h] = mn; }
; #pragma unroll
;         for (int u = 0; u < 8; ++u) { const float p = __builtin_amdgcn_exp2f(s[u] - m[h]); l[h] += p; o[h] = o[h] + vx[u] * p; } }
; __device__ __forceinline__ float smp_merge(float (&m)[4], float (&l)[4], f32x4 (&o)[4], LAS unsigned char* lds, int tid) {
;     const int lane = tid & 63, w = tid >> 6, kq = lane >> 4, d4 = lane & 15, hh = lane >> 5;
;     LAS float* pm = (LAS float*)(lds + S_PM); LAS float* pl = (LAS float*)(lds + S_PL); LAS float* po = (LAS float*)(lds + S_PO);
; #pragma unroll
;     for (int h = 0; h < 4; ++h) {
;         { const float m2 = lane_xor<16>(m[h]), l2 = lane_xor<16>(l[h]); f32x4 o2; o2[0] = lane_xor<16>(o[h][0]); o2[1] = lane_xor<16>(o[h][1]); o2[2] = lane_xor<16>(o[h][2]); o2[3] = lane_xor<16>(o[h][3]);
;           const float mt = fmaxf(m[h], m2), a1 = __builtin_amdgcn_exp2f(m[h] - mt), a2 = __builtin_amdgcn_exp2f(m2 - mt); l[h] = l[h] * a1 + l2 * a2; o[h] = o[h] * a1 + o2 * a2; m[h] = mt; }
;         { const float m2 = xhalf_other(m[h], hh), l2 = xhalf_other(l[h], hh); f32x4 o2; o2[0] = xhalf_other(o[h][0], hh); o2[1] = xhalf_other(o[h][1], hh); o2[2] = xhalf_other(o[h][2], hh); o2[3] = xhalf_other(o[h][3], hh);
;           const float mt = fmaxf(m[h], m2), a1 = __builtin_amdgcn_exp2f(m[h] - mt), a2 = __builtin_amdgcn_exp2f(m2 - mt); l[h] = l[h] * a1 + l2 * a2; o[h] = o[h] * a1 + o2 * a2; m[h] = mt; }
;         if (kq == 0) { *(LAS f32x4*)(po + (w * 4 + h) * 64 + 4 * d4) = o[h]; if (d4 == 0) { pm[w * 4 + h] = m[h]; pl[w * 4 + h] = l[h]; } }
	v_pk_fma_f32 v[64:65], v[14:15], v[62:63], v[64:65] op_sel_hi:[1,0,1]
	v_pk_fma_f32 v[46:47], v[28:29], v[90:91], v[46:47] op_sel_hi:[1,0,1]
	v_exp_f32_e32 v82, v61
	v_sub_f32_e32 v61, v137, v5
	v_pk_fma_f32 v[64:65], v[22:23], v[80:81], v[64:65] op_sel_hi:[1,0,1]
	v_pk_fma_f32 v[46:47], v[32:33], v[92:93], v[46:47] op_sel_hi:[1,0,1]
	v_mov_b32_e32 v83, v80
	v_exp_f32_e32 v80, v61
	v_sub_f32_e32 v61, v138, v5
	v_pk_fma_f32 v[64:65], v[26:27], v[88:89], v[64:65] op_sel_hi:[1,0,1]
	v_pk_fma_f32 v[46:47], v[36:37], v[110:111], v[46:47] op_sel_hi:[1,0,1]
	v_mov_b32_e32 v81, v88
	v_exp_f32_e32 v88, v61
	v_sub_f32_e32 v61, v139, v5
	v_pk_fma_f32 v[64:65], v[30:31], v[90:91], v[64:65] op_sel_hi:[1,0,1]
	v_pk_fma_f32 v[46:47], v[40:41], v[112:113], v[46:47] op_sel_hi:[1,0,1]
	v_mov_b32_e32 v89, v90
	v_exp_f32_e32 v90, v61
	v_sub_f32_e32 v61, v140, v5
	v_pk_fma_f32 v[64:65], v[34:35], v[92:93], v[64:65] op_sel_hi:[1,0,1]
	v_mov_b32_e32 v91, v92
	v_exp_f32_e32 v92, v61
	v_sub_f32_e32 v61, v141, v5
	v_pk_fma_f32 v[62:63], v[76:77], v[114:115], v[46:47] op_sel_hi:[1,0,1]
	v_cndmask_b32_e64 v47, v87, v57, s[24:25]
	v_cndmask_b32_e64 v46, v86, v56, s[24:25]
	v_cndmask_b32_e64 v57, v85, v59, s[24:25]
	v_cndmask_b32_e64 v56, v84, v58, s[24:25]
	v_pk_fma_f32 v[12:13], v[12:13], v[60:61], v[56:57] op_sel_hi:[1,0,1]
	v_pk_fma_f32 v[14:15], v[14:15], v[60:61], v[46:47] op_sel_hi:[1,0,1]
	v_pk_add_f32 v[44:45], v[82:83], v[44:45]
	v_pk_fma_f32 v[14:15], v[22:23], v[82:83], v[14:15] op_sel_hi:[1,0,1]
	v_pk_fma_f32 v[12:13], v[20:21], v[82:83], v[12:13] op_sel_hi:[1,0,1]
	v_pk_fma_f32 v[64:65], v[38:39], v[110:111], v[64:65] op_sel_hi:[1,0,1]
	v_pk_add_f32 v[44:45], v[80:81], v[44:45]
	v_mov_b32_e32 v93, v110
	v_exp_f32_e32 v110, v61
	v_pk_fma_f32 v[12:13], v[24:25], v[80:81], v[12:13] op_sel_hi:[1,0,1]
	v_pk_fma_f32 v[14:15], v[26:27], v[80:81], v[14:15] op_sel_hi:[1,0,1]
	v_sub_f32_e32 v20, v142, v5
	v_pk_add_f32 v[44:45], v[88:89], v[44:45]
	v_pk_fma_f32 v[14:15], v[30:31], v[88:89], v[14:15] op_sel_hi:[1,0,1]
	v_pk_fma_f32 v[12:13], v[28:29], v[88:89], v[12:13] op_sel_hi:[1,0,1]
	v_exp_f32_e32 v20, v20
	v_pk_add_f32 v[44:45], v[90:91], v[44:45]
	v_pk_fma_f32 v[12:13], v[32:33], v[90:91], v[12:13] op_sel_hi:[1,0,1]
	v_pk_fma_f32 v[14:15], v[34:35], v[90:91], v[14:15] op_sel_hi:[1,0,1]
	v_pk_add_f32 v[44:45], v[92:93], v[44:45]
	v_mov_b32_e32 v111, v112
	v_pk_fma_f32 v[14:15], v[38:39], v[92:93], v[14:15] op_sel_hi:[1,0,1]
	v_pk_fma_f32 v[12:13], v[36:37], v[92:93], v[12:13] op_sel_hi:[1,0,1]
	v_pk_fma_f32 v[64:65], v[42:43], v[112:113], v[64:65] op_sel_hi:[1,0,1]
	v_pk_add_f32 v[44:45], v[110:111], v[44:45]
	v_pk_fma_f32 v[12:13], v[40:41], v[110:111], v[12:13] op_sel_hi:[1,0,1]
	v_pk_fma_f32 v[14:15], v[42:43], v[110:111], v[14:15] op_sel_hi:[1,0,1]
	v_mov_b32_e32 v21, v114
	v_pk_fma_f32 v[64:65], v[78:79], v[114:115], v[64:65] op_sel_hi:[1,0,1]
	v_pk_add_f32 v[60:61], v[20:21], v[44:45]
	v_pk_fma_f32 v[56:57], v[78:79], v[20:21], v[14:15] op_sel_hi:[1,0,1]
	v_pk_fma_f32 v[58:59], v[76:77], v[20:21], v[12:13] op_sel_hi:[1,0,1]
	s_cbranch_vccz .LBB0_2641
	ds_swizzle_b32 v0, v97 offset:swizzle(SWAP,16)
	v_max_f32_e32 v7, v97, v97
	ds_swizzle_b32 v2, v72 offset:swizzle(SWAP,16)
	ds_swizzle_b32 v3, v73 offset:swizzle(SWAP,16)
	ds_swizzle_b32 v9, v71 offset:swizzle(SWAP,16)
	s_waitcnt lgkmcnt(3)
	v_max_f32_e32 v8, v0, v0
	v_max_f32_e32 v12, v7, v8
	v_sub_f32_e32 v7, v97, v12
	v_sub_f32_e32 v0, v0, v12
	ds_swizzle_b32 v6, v74 offset:swizzle(SWAP,16)
	v_exp_f32_e32 v0, v0
	v_exp_f32_e32 v8, v7
	ds_swizzle_b32 v7, v75 offset:swizzle(SWAP,16)
	v_mov_b32_e32 v18, v12
	s_waitcnt lgkmcnt(3)
	v_pk_mul_f32 v[10:11], v[0:1], v[2:3] op_sel_hi:[0,1]
	s_waitcnt lgkmcnt(2)
	v_mul_f32_e32 v13, v0, v9
	v_fmac_f32_e32 v13, v71, v8
	s_waitcnt lgkmcnt(0)
	v_pk_mul_f32 v[2:3], v[0:1], v[6:7] op_sel_hi:[0,1]
	v_pk_fma_f32 v[6:7], v[72:73], v[8:9], v[10:11] op_sel_hi:[1,0,1]
	v_pk_fma_f32 v[2:3], v[74:75], v[8:9], v[2:3] op_sel_hi:[1,0,1]
	v_mov_b32_e32 v9, v6
	v_mov_b32_e32 v8, v6
	s_nop 1
	v_permlane32_swap_b32_e32 v9, v8
	v_mov_b32_e32 v10, v7
	v_mov_b32_e32 v9, v7
	s_nop 1
	v_permlane32_swap_b32_e32 v10, v9
	v_mov_b32_e32 v11, v2
	v_mov_b32_e32 v10, v2
	s_nop 1
	v_permlane32_swap_b32_e32 v11, v10
	v_mov_b32_e32 v0, v12
	v_mov_b32_e32 v14, v13
	v_mov_b32_e32 v15, v13
	v_mov_b32_e32 v19, v3
	v_mov_b32_e32 v11, v3
	v_permlane32_swap_b32_e32 v0, v18
	v_permlane32_swap_b32_e32 v14, v15
	v_permlane32_swap_b32_e32 v19, v11
	s_and_saveexec_b64 s[0:1], s[12:13]
	s_cbranch_execz .LBB0_2645
	v_cndmask_b32_e64 v0, v0, v18, s[10:11]
	v_max_f32_e32 v18, v0, v0
	v_max_f32_e32 v19, v12, v12
	v_max_f32_e32 v18, v19, v18
	v_sub_f32_e32 v0, v0, v18
	v_exp_f32_e32 v0, v0
	v_sub_f32_e32 v12, v12, v18
	v_exp_f32_e32 v12, v12
	v_pk_mul_f32 v[20:21], v[0:1], v[8:9] op_sel_hi:[0,1]
	v_pk_mul_f32 v[8:9], v[0:1], v[10:11] op_sel_hi:[0,1]
	v_pk_fma_f32 v[8:9], v[2:3], v[12:13], v[8:9] op_sel_hi:[1,0,1]
	v_pk_fma_f32 v[6:7], v[6:7], v[12:13], v[20:21] op_sel_hi:[1,0,1]
	ds_write_b128 v99, v[6:9]
	s_and_b64 exec, exec, s[8:9]
	s_cbranch_execz .LBB0_2645
	v_cndmask_b32_e64 v2, v14, v15, s[10:11]
	v_mul_f32_e32 v0, v0, v2
	v_lshl_add_u32 v2, v98, 2, 0
	v_add_u32_e32 v3, 0x21c80, v2
	v_add_u32_e32 v2, 0x21c00, v2
	v_fmac_f32_e32 v0, v13, v12
	ds_write_b32 v2, v18
	ds_write_b32 v3, v0
